# GEMM K-loops: LDS-DMA loads use SGPR base + 32-bit VGPR offset form, 16 v_lshl_add_u64 per iteration removed
# speedup vs baseline: 1.0288x; 1.0050x over previous
; #define PG8_STAGE(bufoff, gbase, voff) do { _Pragma("unroll") for (int _i = 0; _i < 2; ++_i) \
;         __builtin_amdgcn_global_load_lds((const unsigned*)((const char*)(gbase) + (voff)[_i]), (PG8_LAS unsigned*)(lds + (bufoff) + ldsw + _i * 8192), 16, 0, 0); } while (0)
; #define PG8_LDA(dst, b, h) do { _Pragma("unroll") for (int m = 0; m < 4; ++m) _Pragma("unroll") for (int k = 0; k < 2; ++k) dst[m][k] = *(const PG8_LAS bf16x8*)(lds + PG8_SA(b, h) + aoff + m * 2048 + k * 1024); } while (0)
; #define PG8_LDB(dst, b, h) do { _Pragma("unroll") for (int n = 0; n < 2; ++n) _Pragma("unroll") for (int k = 0; k < 2; ++k) dst[n][k] = *(const PG8_LAS bf16x8*)(lds + PG8_SB(b, h) + boff + n * 2048 + k * 1024); } while (0)
; #define PG8_MMA(ai, bj, At, Bt) do { __builtin_amdgcn_s_setprio(1); _Pragma("unroll") for (int m = 0; m < 4; ++m) _Pragma("unroll") for (int n = 0; n < 2; ++n) _Pragma("unroll") for (int k = 0; k < 2; ++k) \
;         acc[ai][bj][m][n] = __builtin_amdgcn_mfma_f32_16x16x32_bf16(Bt[n][k], At[m][k], acc[ai][bj][m][n], 0, 0, 0); __builtin_amdgcn_s_setprio(0); } while (0)
; #define PG8_WAIT_V(n) asm volatile("s_waitcnt vmcnt(" #n ")" ::: "memory")
; #define PG8_WAIT_L(n) asm volatile("s_waitcnt lgkmcnt(" #n ")" ::: "memory")
; template <class Epi, class Sched, bool ALIGN_EPI = false, bool SP2 = false>
; __device__ __forceinline__ void gemm_phase(PG8_LAS unsigned char* lds, const Gemm g, const Sched& S, const Epi& E) {
;     ...
;             const bool last = (t == nt - 2);
;             const char* a1 = cA + (size_t)(t + 1) * kstep;
;             const char* a2 = last ? nA : cA + (size_t)(t + 2) * kstep; const char* b2 = last ? nB : cB + (size_t)(t + 2) * kstep;
;             const char* a3 = a2 + kstep; const char* b3 = b2 + kstep;
;             if (last && has_next) S.a_ready(nxt);
;             if constexpr (SP2) {
;             PG8_LDB(B0, 0, 0); PG8_LDB(B1, 0, 1); PG8_SCHED; PG8_LDA(At, 0, 0); PG8_STAGE(PG8_SA(1, 1), a1 + hstep, voffA);
;             PG8_WAIT_V(8); PG8_WAIT_L(0); PG8_BAR; PG8_MMA(0, 0, At, B0); PG8_MMA(0, 1, At, B1); PG8_BAR; PG8_SCHED;
;             PG8_LDA(At, 0, 1); PG8_STAGE(PG8_SB(0, 0), b2, voffB); PG8_STAGE(PG8_SB(0, 1), b2 + hstep, voffB); PG8_STAGE(PG8_SA(0, 0), a2, voffA);
;             PG8_WAIT_V(8); PG8_WAIT_L(0); PG8_BAR; PG8_MMA(1, 0, At, B0); PG8_MMA(1, 1, At, B1); PG8_BAR; PG8_SCHED;
.LBB0_124:
	ds_read_b128 v[150:153], v161
	ds_read_b128 v[154:157], v161 offset:1024
	ds_read_b128 v[166:169], v161 offset:2048
	ds_read_b128 v[170:173], v161 offset:3072
	ds_read_b128 v[174:177], v162
	ds_read_b128 v[178:181], v162 offset:1024
	ds_read_b128 v[182:185], v162 offset:2048
	ds_read_b128 v[186:189], v162 offset:3072
	s_add_u32 s4, s36, 0xfff80080
	s_addc_u32 s5, s37, -1
	s_cmp_eq_u32 s69, 28
	s_cselect_b32 s41, s9, s5
	s_cselect_b32 s40, s27, s4
	s_cselect_b32 s39, s25, s68
	s_cselect_b32 s38, s35, s67
	s_add_i32 m0, s49, 0xc000
	ds_read_b128 v[190:193], v163
	ds_read_b128 v[194:197], v163 offset:1024
	ds_read_b128 v[198:201], v163 offset:2048
	ds_read_b128 v[202:205], v163 offset:3072
	ds_read_b128 v[206:209], v163 offset:4096
	ds_read_b128 v[210:213], v163 offset:5120
	ds_read_b128 v[214:217], v163 offset:6144
	ds_read_b128 v[218:221], v163 offset:7168
	global_load_lds_dwordx4 v140, s[36:37]
	s_add_i32 m0, s49, 0xe000
	s_nop 0
	global_load_lds_dwordx4 v142, s[36:37]
	s_waitcnt vmcnt(8)
	s_waitcnt lgkmcnt(0)
	s_barrier
	s_setprio 1
	s_waitcnt lgkmcnt(0)
	v_mfma_f32_16x16x32_bf16 v[126:129], v[150:153], v[190:193], v[126:129]
	v_mfma_f32_16x16x32_bf16 v[122:125], v[166:169], v[190:193], v[122:125]
	v_mfma_f32_16x16x32_bf16 v[110:113], v[150:153], v[198:201], v[110:113]
	v_mfma_f32_16x16x32_bf16 v[106:109], v[166:169], v[198:201], v[106:109]
	v_mfma_f32_16x16x32_bf16 v[94:97], v[150:153], v[206:209], v[94:97]
	v_mfma_f32_16x16x32_bf16 v[90:93], v[166:169], v[206:209], v[90:93]
	v_mfma_f32_16x16x32_bf16 v[78:81], v[150:153], v[214:217], v[78:81]
	v_mfma_f32_16x16x32_bf16 v[74:77], v[166:169], v[214:217], v[74:77]
	v_mfma_f32_16x16x32_bf16 v[126:129], v[154:157], v[194:197], v[126:129]
	v_mfma_f32_16x16x32_bf16 v[122:125], v[170:173], v[194:197], v[122:125]
	v_mfma_f32_16x16x32_bf16 v[110:113], v[154:157], v[202:205], v[110:113]
	v_mfma_f32_16x16x32_bf16 v[106:109], v[170:173], v[202:205], v[106:109]
	v_mfma_f32_16x16x32_bf16 v[94:97], v[154:157], v[210:213], v[94:97]
	v_mfma_f32_16x16x32_bf16 v[90:93], v[170:173], v[210:213], v[90:93]
	v_mfma_f32_16x16x32_bf16 v[78:81], v[154:157], v[218:221], v[78:81]
	v_mfma_f32_16x16x32_bf16 v[74:77], v[170:173], v[218:221], v[74:77]
	s_setprio 0
	s_setprio 1
	v_mfma_f32_16x16x32_bf16 v[118:121], v[174:177], v[190:193], v[118:121]
	v_mfma_f32_16x16x32_bf16 v[114:117], v[182:185], v[190:193], v[114:117]
	v_mfma_f32_16x16x32_bf16 v[102:105], v[174:177], v[198:201], v[102:105]
	v_mfma_f32_16x16x32_bf16 v[98:101], v[182:185], v[198:201], v[98:101]
	v_mfma_f32_16x16x32_bf16 v[86:89], v[174:177], v[206:209], v[86:89]
	v_mfma_f32_16x16x32_bf16 v[82:85], v[182:185], v[206:209], v[82:85]
	v_mfma_f32_16x16x32_bf16 v[70:73], v[174:177], v[214:217], v[70:73]
	v_mfma_f32_16x16x32_bf16 v[66:69], v[182:185], v[214:217], v[66:69]
	v_mfma_f32_16x16x32_bf16 v[118:121], v[178:181], v[194:197], v[118:121]
	v_mfma_f32_16x16x32_bf16 v[114:117], v[186:189], v[194:197], v[114:117]
	v_mfma_f32_16x16x32_bf16 v[102:105], v[178:181], v[202:205], v[102:105]
	v_mfma_f32_16x16x32_bf16 v[98:101], v[186:189], v[202:205], v[98:101]
	v_mfma_f32_16x16x32_bf16 v[86:89], v[178:181], v[210:213], v[86:89]
	v_mfma_f32_16x16x32_bf16 v[82:85], v[186:189], v[210:213], v[82:85]
	v_mfma_f32_16x16x32_bf16 v[70:73], v[178:181], v[218:221], v[70:73]
	v_mfma_f32_16x16x32_bf16 v[66:69], v[186:189], v[218:221], v[66:69]
	s_setprio 0
	s_barrier
	s_add_i32 s4, s64, s48
	s_mov_b32 m0, s4
	ds_read_b128 v[190:193], v163 offset:16384
	ds_read_b128 v[194:197], v163 offset:17408
	ds_read_b128 v[198:201], v163 offset:18432
	ds_read_b128 v[202:205], v163 offset:19456
	ds_read_b128 v[206:209], v163 offset:20480
	ds_read_b128 v[210:213], v163 offset:21504
	ds_read_b128 v[214:217], v163 offset:22528
	ds_read_b128 v[218:221], v163 offset:23552
	global_load_lds_dwordx4 v132, s[38:39]
	s_add_i32 m0, s4, 0x2000
	s_add_u32 s70, s38, 0x80000
	s_addc_u32 s71, s39, 0
	s_add_i32 s4, s65, s48
	global_load_lds_dwordx4 v136, s[38:39]
	s_mov_b32 m0, s4
	s_nop 0
	global_load_lds_dwordx4 v132, s[70:71]
	s_add_i32 m0, s4, 0x2000
	s_nop 0
	global_load_lds_dwordx4 v136, s[70:71]
	s_mov_b32 m0, s49
	s_nop 0
	global_load_lds_dwordx4 v130, s[40:41]
	s_mov_b32 m0, s50
	s_nop 0
	global_load_lds_dwordx4 v134, s[40:41]
	s_waitcnt vmcnt(8)
	s_waitcnt lgkmcnt(0)
	s_barrier
	s_setprio 1
	s_waitcnt lgkmcnt(0)
	v_mfma_f32_16x16x32_bf16 v[62:65], v[150:153], v[190:193], v[62:65]
	v_mfma_f32_16x16x32_bf16 v[58:61], v[166:169], v[190:193], v[58:61]
	v_mfma_f32_16x16x32_bf16 v[46:49], v[150:153], v[198:201], v[46:49]
	v_mfma_f32_16x16x32_bf16 v[42:45], v[166:169], v[198:201], v[42:45]
	v_mfma_f32_16x16x32_bf16 v[30:33], v[150:153], v[206:209], v[30:33]
	v_mfma_f32_16x16x32_bf16 v[26:29], v[166:169], v[206:209], v[26:29]
	v_mfma_f32_16x16x32_bf16 v[14:17], v[150:153], v[214:217], v[14:17]
	v_mfma_f32_16x16x32_bf16 v[10:13], v[166:169], v[214:217], v[10:13]
	v_mfma_f32_16x16x32_bf16 v[62:65], v[154:157], v[194:197], v[62:65]
	v_mfma_f32_16x16x32_bf16 v[58:61], v[170:173], v[194:197], v[58:61]
	v_mfma_f32_16x16x32_bf16 v[46:49], v[154:157], v[202:205], v[46:49]
	v_mfma_f32_16x16x32_bf16 v[42:45], v[170:173], v[202:205], v[42:45]
	v_mfma_f32_16x16x32_bf16 v[30:33], v[154:157], v[210:213], v[30:33]
	v_mfma_f32_16x16x32_bf16 v[26:29], v[170:173], v[210:213], v[26:29]
	v_mfma_f32_16x16x32_bf16 v[14:17], v[154:157], v[218:221], v[14:17]
	v_mfma_f32_16x16x32_bf16 v[10:13], v[170:173], v[218:221], v[10:13]
	s_setprio 0
	s_setprio 1
	v_mfma_f32_16x16x32_bf16 v[54:57], v[174:177], v[190:193], v[54:57]
	v_mfma_f32_16x16x32_bf16 v[50:53], v[182:185], v[190:193], v[50:53]
	v_mfma_f32_16x16x32_bf16 v[38:41], v[174:177], v[198:201], v[38:41]
	v_mfma_f32_16x16x32_bf16 v[34:37], v[182:185], v[198:201], v[34:37]
	v_mfma_f32_16x16x32_bf16 v[22:25], v[174:177], v[206:209], v[22:25]
	v_mfma_f32_16x16x32_bf16 v[18:21], v[182:185], v[206:209], v[18:21]
	v_mfma_f32_16x16x32_bf16 v[6:9], v[174:177], v[214:217], v[6:9]
	v_mfma_f32_16x16x32_bf16 v[2:5], v[182:185], v[214:217], v[2:5]
	v_mfma_f32_16x16x32_bf16 v[54:57], v[178:181], v[194:197], v[54:57]
	v_mfma_f32_16x16x32_bf16 v[50:53], v[186:189], v[194:197], v[50:53]
	v_mfma_f32_16x16x32_bf16 v[38:41], v[178:181], v[202:205], v[38:41]
	v_mfma_f32_16x16x32_bf16 v[34:37], v[186:189], v[202:205], v[34:37]
	v_mfma_f32_16x16x32_bf16 v[22:25], v[178:181], v[210:213], v[22:25]
	v_mfma_f32_16x16x32_bf16 v[18:21], v[186:189], v[210:213], v[18:21]
	v_mfma_f32_16x16x32_bf16 v[6:9], v[178:181], v[218:221], v[6:9]
	v_mfma_f32_16x16x32_bf16 v[2:5], v[186:189], v[218:221], v[2:5]
	s_setprio 0
	s_barrier
; #define PG8_STAGE(bufoff, gbase, voff) do { _Pragma("unroll") for (int _i = 0; _i < 2; ++_i) \
;         __builtin_amdgcn_global_load_lds((const unsigned*)((const char*)(gbase) + (voff)[_i]), (PG8_LAS unsigned*)(lds + (bufoff) + ldsw + _i * 8192), 16, 0, 0); } while (0)
; #define PG8_LDA(dst, b, h) do { _Pragma("unroll") for (int m = 0; m < 4; ++m) _Pragma("unroll") for (int k = 0; k < 2; ++k) dst[m][k] = *(const PG8_LAS bf16x8*)(lds + PG8_SA(b, h) + aoff + m * 2048 + k * 1024); } while (0)
; #define PG8_LDB(dst, b, h) do { _Pragma("unroll") for (int n = 0; n < 2; ++n) _Pragma("unroll") for (int k = 0; k < 2; ++k) dst[n][k] = *(const PG8_LAS bf16x8*)(lds + PG8_SB(b, h) + boff + n * 2048 + k * 1024); } while (0)
; #define PG8_MMA(ai, bj, At, Bt) do { __builtin_amdgcn_s_setprio(1); _Pragma("unroll") for (int m = 0; m < 4; ++m) _Pragma("unroll") for (int n = 0; n < 2; ++n) _Pragma("unroll") for (int k = 0; k < 2; ++k) \
;         acc[ai][bj][m][n] = __builtin_amdgcn_mfma_f32_16x16x32_bf16(Bt[n][k], At[m][k], acc[ai][bj][m][n], 0, 0, 0); __builtin_amdgcn_s_setprio(0); } while (0)
; #define PG8_WAIT_V(n) asm volatile("s_waitcnt vmcnt(" #n ")" ::: "memory")
; #define PG8_WAIT_L(n) asm volatile("s_waitcnt lgkmcnt(" #n ")" ::: "memory")
; #define PG8_BAR __builtin_amdgcn_s_barrier()
; #define PG8_SCHED __builtin_amdgcn_sched_barrier(0)
; template <class Epi, class Sched, bool ALIGN_EPI = false, bool SP2 = false>
; __device__ __forceinline__ void gemm_phase(PG8_LAS unsigned char* lds, const Gemm g, const Sched& S, const Epi& E) {
;     ...
;             PG8_LDB(B0, 1, 0); PG8_LDB(B1, 1, 1); PG8_SCHED; PG8_LDA(At, 1, 0); PG8_STAGE(PG8_SA(0, 1), a2 + hstep, voffA);
;             PG8_WAIT_V(8); PG8_WAIT_L(0); PG8_BAR; PG8_MMA(0, 0, At, B0); PG8_MMA(0, 1, At, B1); PG8_BAR; PG8_SCHED;
;             PG8_LDA(At, 1, 1); PG8_STAGE(PG8_SB(1, 0), b3, voffB); PG8_STAGE(PG8_SB(1, 1), b3 + hstep, voffB); PG8_STAGE(PG8_SA(1, 0), a3, voffA);
;             PG8_WAIT_V(8); PG8_WAIT_L(0); PG8_BAR; PG8_MMA(1, 0, At, B0); PG8_MMA(1, 1, At, B1); PG8_BAR; PG8_SCHED;
	s_add_i32 s4, 0, 0x18000
	v_add_u32_e32 v138, s4, v159
	s_add_i32 s5, 0, 0x1c000
	ds_read_b128 v[150:153], v138
	ds_read_b128 v[154:157], v138 offset:1024
	ds_read_b128 v[166:169], v138 offset:2048
	ds_read_b128 v[170:173], v138 offset:3072
	v_add_u32_e32 v138, s5, v159
	ds_read_b128 v[174:177], v138
	ds_read_b128 v[178:181], v138 offset:1024
	ds_read_b128 v[182:185], v138 offset:2048
	ds_read_b128 v[186:189], v138 offset:3072
	s_add_u32 s70, s40, 0x80000
	s_addc_u32 s71, s41, 0
	s_mov_b32 m0, s51
	ds_read_b128 v[190:193], v163 offset:32768
	ds_read_b128 v[194:197], v163 offset:33792
	ds_read_b128 v[198:201], v163 offset:34816
	ds_read_b128 v[202:205], v163 offset:35840
	ds_read_b128 v[206:209], v163 offset:36864
	ds_read_b128 v[210:213], v163 offset:37888
	ds_read_b128 v[214:217], v163 offset:38912
	ds_read_b128 v[218:221], v163 offset:39936
	global_load_lds_dwordx4 v130, s[70:71]
	s_mov_b32 m0, s52
	s_nop 0
	global_load_lds_dwordx4 v134, s[70:71]
	s_waitcnt vmcnt(8)
	s_waitcnt lgkmcnt(0)
	s_barrier
	s_setprio 1
	s_waitcnt lgkmcnt(0)
	v_mfma_f32_16x16x32_bf16 v[126:129], v[150:153], v[190:193], v[126:129]
	v_mfma_f32_16x16x32_bf16 v[122:125], v[166:169], v[190:193], v[122:125]
	v_mfma_f32_16x16x32_bf16 v[110:113], v[150:153], v[198:201], v[110:113]
	v_mfma_f32_16x16x32_bf16 v[106:109], v[166:169], v[198:201], v[106:109]
	v_mfma_f32_16x16x32_bf16 v[94:97], v[150:153], v[206:209], v[94:97]
	v_mfma_f32_16x16x32_bf16 v[90:93], v[166:169], v[206:209], v[90:93]
	v_mfma_f32_16x16x32_bf16 v[78:81], v[150:153], v[214:217], v[78:81]
	v_mfma_f32_16x16x32_bf16 v[74:77], v[166:169], v[214:217], v[74:77]
	v_mfma_f32_16x16x32_bf16 v[126:129], v[154:157], v[194:197], v[126:129]
	v_mfma_f32_16x16x32_bf16 v[122:125], v[170:173], v[194:197], v[122:125]
	v_mfma_f32_16x16x32_bf16 v[110:113], v[154:157], v[202:205], v[110:113]
	v_mfma_f32_16x16x32_bf16 v[106:109], v[170:173], v[202:205], v[106:109]
	v_mfma_f32_16x16x32_bf16 v[94:97], v[154:157], v[210:213], v[94:97]
	v_mfma_f32_16x16x32_bf16 v[90:93], v[170:173], v[210:213], v[90:93]
	v_mfma_f32_16x16x32_bf16 v[78:81], v[154:157], v[218:221], v[78:81]
	v_mfma_f32_16x16x32_bf16 v[74:77], v[170:173], v[218:221], v[74:77]
	s_setprio 0
	s_setprio 1
	v_mfma_f32_16x16x32_bf16 v[118:121], v[174:177], v[190:193], v[118:121]
	v_mfma_f32_16x16x32_bf16 v[114:117], v[182:185], v[190:193], v[114:117]
	v_mfma_f32_16x16x32_bf16 v[102:105], v[174:177], v[198:201], v[102:105]
	v_mfma_f32_16x16x32_bf16 v[98:101], v[182:185], v[198:201], v[98:101]
	v_mfma_f32_16x16x32_bf16 v[86:89], v[174:177], v[206:209], v[86:89]
	v_mfma_f32_16x16x32_bf16 v[82:85], v[182:185], v[206:209], v[82:85]
	v_mfma_f32_16x16x32_bf16 v[70:73], v[174:177], v[214:217], v[70:73]
	v_mfma_f32_16x16x32_bf16 v[66:69], v[182:185], v[214:217], v[66:69]
	v_mfma_f32_16x16x32_bf16 v[118:121], v[178:181], v[194:197], v[118:121]
	v_mfma_f32_16x16x32_bf16 v[114:117], v[186:189], v[194:197], v[114:117]
	v_mfma_f32_16x16x32_bf16 v[102:105], v[178:181], v[202:205], v[102:105]
	v_mfma_f32_16x16x32_bf16 v[98:101], v[186:189], v[202:205], v[98:101]
	v_mfma_f32_16x16x32_bf16 v[86:89], v[178:181], v[210:213], v[86:89]
	v_mfma_f32_16x16x32_bf16 v[82:85], v[186:189], v[210:213], v[82:85]
	v_mfma_f32_16x16x32_bf16 v[70:73], v[178:181], v[218:221], v[70:73]
	v_mfma_f32_16x16x32_bf16 v[66:69], v[186:189], v[218:221], v[66:69]
	s_setprio 0
	s_barrier
	s_add_i32 s4, s4, s48
	s_add_i32 m0, s4, 0xffffff80
	ds_read_b128 v[190:193], v163 offset:49152
	ds_read_b128 v[194:197], v163 offset:50176
	ds_read_b128 v[198:201], v163 offset:51200
	ds_read_b128 v[202:205], v163 offset:52224
	ds_read_b128 v[206:209], v163 offset:53248
	ds_read_b128 v[210:213], v163 offset:54272
	ds_read_b128 v[214:217], v163 offset:55296
	ds_read_b128 v[218:221], v163 offset:56320
	global_load_lds_dwordx4 v132, s[38:39] offset:128
	s_add_i32 m0, s4, 0x1f80
	s_nop 0
	global_load_lds_dwordx4 v136, s[38:39] offset:128
	s_add_u32 s38, s38, 0x80080
	s_addc_u32 s39, s39, 0
	s_add_i32 s4, s5, s48
	s_mov_b32 m0, s4
	s_nop 0
	global_load_lds_dwordx4 v132, s[38:39]
	s_add_i32 m0, s4, 0x2000
	s_nop 0
	global_load_lds_dwordx4 v136, s[38:39]
	s_add_i32 m0, s58, 0xffffff80
	s_nop 0
	global_load_lds_dwordx4 v130, s[40:41] offset:128
	s_add_i32 m0, s59, 0xffffff80
	s_nop 0
	global_load_lds_dwordx4 v134, s[40:41] offset:128
	s_waitcnt vmcnt(8)
	s_waitcnt lgkmcnt(0)
	s_barrier
	s_setprio 1
	s_waitcnt lgkmcnt(0)
	v_mfma_f32_16x16x32_bf16 v[62:65], v[150:153], v[190:193], v[62:65]
	v_mfma_f32_16x16x32_bf16 v[58:61], v[166:169], v[190:193], v[58:61]
	v_mfma_f32_16x16x32_bf16 v[46:49], v[150:153], v[198:201], v[46:49]
	v_mfma_f32_16x16x32_bf16 v[42:45], v[166:169], v[198:201], v[42:45]
	v_mfma_f32_16x16x32_bf16 v[30:33], v[150:153], v[206:209], v[30:33]
	v_mfma_f32_16x16x32_bf16 v[26:29], v[166:169], v[206:209], v[26:29]
	v_mfma_f32_16x16x32_bf16 v[14:17], v[150:153], v[214:217], v[14:17]
	v_mfma_f32_16x16x32_bf16 v[10:13], v[166:169], v[214:217], v[10:13]
	v_mfma_f32_16x16x32_bf16 v[62:65], v[154:157], v[194:197], v[62:65]
	v_mfma_f32_16x16x32_bf16 v[58:61], v[170:173], v[194:197], v[58:61]
	v_mfma_f32_16x16x32_bf16 v[46:49], v[154:157], v[202:205], v[46:49]
	v_mfma_f32_16x16x32_bf16 v[42:45], v[170:173], v[202:205], v[42:45]
	v_mfma_f32_16x16x32_bf16 v[30:33], v[154:157], v[210:213], v[30:33]
	v_mfma_f32_16x16x32_bf16 v[26:29], v[170:173], v[210:213], v[26:29]
	v_mfma_f32_16x16x32_bf16 v[14:17], v[154:157], v[218:221], v[14:17]
	v_mfma_f32_16x16x32_bf16 v[10:13], v[170:173], v[218:221], v[10:13]
	s_setprio 0
	s_setprio 1
	v_mfma_f32_16x16x32_bf16 v[54:57], v[174:177], v[190:193], v[54:57]
	v_mfma_f32_16x16x32_bf16 v[50:53], v[182:185], v[190:193], v[50:53]
	v_mfma_f32_16x16x32_bf16 v[38:41], v[174:177], v[198:201], v[38:41]
	v_mfma_f32_16x16x32_bf16 v[34:37], v[182:185], v[198:201], v[34:37]
	v_mfma_f32_16x16x32_bf16 v[22:25], v[174:177], v[206:209], v[22:25]
	v_mfma_f32_16x16x32_bf16 v[18:21], v[182:185], v[206:209], v[18:21]
	v_mfma_f32_16x16x32_bf16 v[6:9], v[174:177], v[214:217], v[6:9]
	v_mfma_f32_16x16x32_bf16 v[2:5], v[182:185], v[214:217], v[2:5]
	v_mfma_f32_16x16x32_bf16 v[54:57], v[178:181], v[194:197], v[54:57]
	v_mfma_f32_16x16x32_bf16 v[50:53], v[186:189], v[194:197], v[50:53]
	v_mfma_f32_16x16x32_bf16 v[38:41], v[178:181], v[202:205], v[38:41]
	v_mfma_f32_16x16x32_bf16 v[34:37], v[186:189], v[202:205], v[34:37]
	v_mfma_f32_16x16x32_bf16 v[22:25], v[178:181], v[210:213], v[22:25]
	v_mfma_f32_16x16x32_bf16 v[18:21], v[186:189], v[210:213], v[18:21]
	v_mfma_f32_16x16x32_bf16 v[6:9], v[178:181], v[218:221], v[6:9]
	v_mfma_f32_16x16x32_bf16 v[2:5], v[186:189], v[218:221], v[2:5]
	s_setprio 0
	s_barrier
	s_add_i32 s69, s69, 2
	s_add_u32 s36, s36, 0x100
	s_addc_u32 s37, s37, 0
	s_add_u32 s67, s67, 0x100
	s_addc_u32 s68, s68, 0
	s_cmp_gt_u32 s69, 29
	s_cbranch_scc0 .LBB0_124
	s_and_b64 vcc, exec, s[22:23]
	s_cbranch_vccz .LBB0_127
	s_barrier

; #define PG8_STAGE(bufoff, gbase, voff) do { _Pragma("unroll") for (int _i = 0; _i < 2; ++_i) \
;         __builtin_amdgcn_global_load_lds((const unsigned*)((const char*)(gbase) + (voff)[_i]), (PG8_LAS unsigned*)(lds + (bufoff) + ldsw + _i * 8192), 16, 0, 0); } while (0)
; #define PG8_LDA(dst, b, h) do { _Pragma("unroll") for (int m = 0; m < 4; ++m) _Pragma("unroll") for (int k = 0; k < 2; ++k) dst[m][k] = *(const PG8_LAS bf16x8*)(lds + PG8_SA(b, h) + aoff + m * 2048 + k * 1024); } while (0)
; #define PG8_LDB(dst, b, h) do { _Pragma("unroll") for (int n = 0; n < 2; ++n) _Pragma("unroll") for (int k = 0; k < 2; ++k) dst[n][k] = *(const PG8_LAS bf16x8*)(lds + PG8_SB(b, h) + boff + n * 2048 + k * 1024); } while (0)
; #define PG8_MMA(ai, bj, At, Bt) do { __builtin_amdgcn_s_setprio(1); _Pragma("unroll") for (int m = 0; m < 4; ++m) _Pragma("unroll") for (int n = 0; n < 2; ++n) _Pragma("unroll") for (int k = 0; k < 2; ++k) \
;         acc[ai][bj][m][n] = __builtin_amdgcn_mfma_f32_16x16x32_bf16(Bt[n][k], At[m][k], acc[ai][bj][m][n], 0, 0, 0); __builtin_amdgcn_s_setprio(0); } while (0)
; #define PG8_WAIT_V(n) asm volatile("s_waitcnt vmcnt(" #n ")" ::: "memory")
; #define PG8_WAIT_L(n) asm volatile("s_waitcnt lgkmcnt(" #n ")" ::: "memory")
; template <class Epi, class Sched, bool ALIGN_EPI = false, bool SP2 = false>
; __device__ __forceinline__ void gemm_phase(PG8_LAS unsigned char* lds, const Gemm g, const Sched& S, const Epi& E) {
;     ...
;             const bool last = (t == nt - 2);
;             const char* a1 = cA + (size_t)(t + 1) * kstep;
;             const char* a2 = last ? nA : cA + (size_t)(t + 2) * kstep; const char* b2 = last ? nB : cB + (size_t)(t + 2) * kstep;
;             const char* a3 = a2 + kstep; const char* b3 = b2 + kstep;
;             if (last && has_next) S.a_ready(nxt);
;             if constexpr (SP2) {
;             PG8_LDB(B0, 0, 0); PG8_LDB(B1, 0, 1); PG8_SCHED; PG8_LDA(At, 0, 0); PG8_STAGE(PG8_SA(1, 1), a1 + hstep, voffA);
;             PG8_WAIT_V(8); PG8_WAIT_L(0); PG8_BAR; PG8_MMA(0, 0, At, B0); PG8_MMA(0, 1, At, B1); PG8_BAR; PG8_SCHED;
;             PG8_LDA(At, 0, 1); PG8_STAGE(PG8_SB(0, 0), b2, voffB); PG8_STAGE(PG8_SB(0, 1), b2 + hstep, voffB); PG8_STAGE(PG8_SA(0, 0), a2, voffA);
;             PG8_WAIT_V(8); PG8_WAIT_L(0); PG8_BAR; PG8_MMA(1, 0, At, B0); PG8_MMA(1, 1, At, B1); PG8_BAR; PG8_SCHED;
.LBB0_763:
	ds_read_b128 v[154:157], v150
	ds_read_b128 v[158:161], v150 offset:1024
	ds_read_b128 v[162:165], v150 offset:2048
	ds_read_b128 v[166:169], v150 offset:3072
	ds_read_b128 v[170:173], v151
	ds_read_b128 v[174:177], v151 offset:1024
	ds_read_b128 v[178:181], v151 offset:2048
	ds_read_b128 v[182:185], v151 offset:3072
	s_add_u32 s4, s40, 0xfff80080
	s_addc_u32 s5, s41, -1
	s_cmp_eq_u32 s78, 28
	s_cselect_b32 s51, s31, s5
	s_cselect_b32 s50, s74, s4
	s_cselect_b32 s49, s29, s77
	s_cselect_b32 s48, s75, s76
	s_add_i32 m0, s39, 0xc000
	ds_read_b128 v[186:189], v152
	ds_read_b128 v[190:193], v152 offset:1024
	ds_read_b128 v[194:197], v152 offset:2048
	ds_read_b128 v[198:201], v152 offset:3072
	ds_read_b128 v[202:205], v152 offset:4096
	ds_read_b128 v[206:209], v152 offset:5120
	ds_read_b128 v[210:213], v152 offset:6144
	ds_read_b128 v[214:217], v152 offset:7168
	global_load_lds_dwordx4 v138, s[40:41]
	s_add_i32 m0, s39, 0xe000
	s_nop 0
	global_load_lds_dwordx4 v140, s[40:41]
	s_waitcnt vmcnt(8)
	s_waitcnt lgkmcnt(0)
	s_barrier
	s_setprio 1
	s_waitcnt lgkmcnt(0)
	v_mfma_f32_16x16x32_bf16 v[126:129], v[154:157], v[186:189], v[126:129]
	v_mfma_f32_16x16x32_bf16 v[122:125], v[162:165], v[186:189], v[122:125]
	v_mfma_f32_16x16x32_bf16 v[114:117], v[154:157], v[194:197], v[114:117]
	v_mfma_f32_16x16x32_bf16 v[106:109], v[162:165], v[194:197], v[106:109]
	v_mfma_f32_16x16x32_bf16 v[98:101], v[154:157], v[202:205], v[98:101]
	v_mfma_f32_16x16x32_bf16 v[90:93], v[162:165], v[202:205], v[90:93]
	v_mfma_f32_16x16x32_bf16 v[82:85], v[154:157], v[210:213], v[82:85]
	v_mfma_f32_16x16x32_bf16 v[74:77], v[162:165], v[210:213], v[74:77]
	v_mfma_f32_16x16x32_bf16 v[126:129], v[158:161], v[190:193], v[126:129]
	v_mfma_f32_16x16x32_bf16 v[122:125], v[166:169], v[190:193], v[122:125]
	v_mfma_f32_16x16x32_bf16 v[114:117], v[158:161], v[198:201], v[114:117]
	v_mfma_f32_16x16x32_bf16 v[106:109], v[166:169], v[198:201], v[106:109]
	v_mfma_f32_16x16x32_bf16 v[98:101], v[158:161], v[206:209], v[98:101]
	v_mfma_f32_16x16x32_bf16 v[90:93], v[166:169], v[206:209], v[90:93]
	v_mfma_f32_16x16x32_bf16 v[82:85], v[158:161], v[214:217], v[82:85]
	v_mfma_f32_16x16x32_bf16 v[74:77], v[166:169], v[214:217], v[74:77]
	s_setprio 0
	s_setprio 1
	v_mfma_f32_16x16x32_bf16 v[118:121], v[170:173], v[186:189], v[118:121]
	v_mfma_f32_16x16x32_bf16 v[110:113], v[178:181], v[186:189], v[110:113]
	v_mfma_f32_16x16x32_bf16 v[102:105], v[170:173], v[194:197], v[102:105]
	v_mfma_f32_16x16x32_bf16 v[94:97], v[178:181], v[194:197], v[94:97]
	v_mfma_f32_16x16x32_bf16 v[86:89], v[170:173], v[202:205], v[86:89]
	v_mfma_f32_16x16x32_bf16 v[78:81], v[178:181], v[202:205], v[78:81]
	v_mfma_f32_16x16x32_bf16 v[70:73], v[170:173], v[210:213], v[70:73]
	v_mfma_f32_16x16x32_bf16 v[66:69], v[178:181], v[210:213], v[66:69]
	v_mfma_f32_16x16x32_bf16 v[118:121], v[174:177], v[190:193], v[118:121]
	v_mfma_f32_16x16x32_bf16 v[110:113], v[182:185], v[190:193], v[110:113]
	v_mfma_f32_16x16x32_bf16 v[102:105], v[174:177], v[198:201], v[102:105]
	v_mfma_f32_16x16x32_bf16 v[94:97], v[182:185], v[198:201], v[94:97]
	v_mfma_f32_16x16x32_bf16 v[86:89], v[174:177], v[206:209], v[86:89]
	v_mfma_f32_16x16x32_bf16 v[78:81], v[182:185], v[206:209], v[78:81]
	v_mfma_f32_16x16x32_bf16 v[70:73], v[174:177], v[214:217], v[70:73]
	v_mfma_f32_16x16x32_bf16 v[66:69], v[182:185], v[214:217], v[66:69]
	s_setprio 0
	s_barrier
	s_add_i32 s4, s67, s58
	s_mov_b32 m0, s4
	ds_read_b128 v[186:189], v152 offset:16384
	ds_read_b128 v[190:193], v152 offset:17408
	ds_read_b128 v[194:197], v152 offset:18432
	ds_read_b128 v[198:201], v152 offset:19456
	ds_read_b128 v[202:205], v152 offset:20480
	ds_read_b128 v[206:209], v152 offset:21504
	ds_read_b128 v[210:213], v152 offset:22528
	ds_read_b128 v[214:217], v152 offset:23552
	global_load_lds_dwordx4 v132, s[48:49]
	s_add_i32 m0, s4, 0x2000
	s_add_u32 s4, s48, 0x80000
	s_addc_u32 s5, s49, 0
	s_add_i32 s79, s68, s58
	global_load_lds_dwordx4 v136, s[48:49]
	s_mov_b32 m0, s79
	s_nop 0
	global_load_lds_dwordx4 v132, s[4:5]
	s_add_i32 m0, s79, 0x2000
	s_nop 0
	global_load_lds_dwordx4 v136, s[4:5]
	s_mov_b32 m0, s39
	s_nop 0
	global_load_lds_dwordx4 v130, s[50:51]
	s_mov_b32 m0, s59
	s_nop 0
	global_load_lds_dwordx4 v134, s[50:51]
	s_waitcnt vmcnt(8)
	s_waitcnt lgkmcnt(0)
	s_barrier
	s_setprio 1
	s_waitcnt lgkmcnt(0)
	v_mfma_f32_16x16x32_bf16 v[62:65], v[154:157], v[186:189], v[62:65]
	v_mfma_f32_16x16x32_bf16 v[58:61], v[162:165], v[186:189], v[58:61]
	v_mfma_f32_16x16x32_bf16 v[50:53], v[154:157], v[194:197], v[50:53]
	v_mfma_f32_16x16x32_bf16 v[42:45], v[162:165], v[194:197], v[42:45]
	v_mfma_f32_16x16x32_bf16 v[34:37], v[154:157], v[202:205], v[34:37]
	v_mfma_f32_16x16x32_bf16 v[26:29], v[162:165], v[202:205], v[26:29]
	v_mfma_f32_16x16x32_bf16 v[18:21], v[154:157], v[210:213], v[18:21]
	v_mfma_f32_16x16x32_bf16 v[10:13], v[162:165], v[210:213], v[10:13]
	v_mfma_f32_16x16x32_bf16 v[62:65], v[158:161], v[190:193], v[62:65]
	v_mfma_f32_16x16x32_bf16 v[58:61], v[166:169], v[190:193], v[58:61]
	v_mfma_f32_16x16x32_bf16 v[50:53], v[158:161], v[198:201], v[50:53]
	v_mfma_f32_16x16x32_bf16 v[42:45], v[166:169], v[198:201], v[42:45]
	v_mfma_f32_16x16x32_bf16 v[34:37], v[158:161], v[206:209], v[34:37]
	v_mfma_f32_16x16x32_bf16 v[26:29], v[166:169], v[206:209], v[26:29]
	v_mfma_f32_16x16x32_bf16 v[18:21], v[158:161], v[214:217], v[18:21]
	v_mfma_f32_16x16x32_bf16 v[10:13], v[166:169], v[214:217], v[10:13]
	s_setprio 0
	s_setprio 1
	v_mfma_f32_16x16x32_bf16 v[54:57], v[170:173], v[186:189], v[54:57]
	v_mfma_f32_16x16x32_bf16 v[46:49], v[178:181], v[186:189], v[46:49]
	v_mfma_f32_16x16x32_bf16 v[38:41], v[170:173], v[194:197], v[38:41]
	v_mfma_f32_16x16x32_bf16 v[30:33], v[178:181], v[194:197], v[30:33]
	v_mfma_f32_16x16x32_bf16 v[22:25], v[170:173], v[202:205], v[22:25]
	v_mfma_f32_16x16x32_bf16 v[14:17], v[178:181], v[202:205], v[14:17]
	v_mfma_f32_16x16x32_bf16 v[6:9], v[170:173], v[210:213], v[6:9]
	v_mfma_f32_16x16x32_bf16 v[2:5], v[178:181], v[210:213], v[2:5]
	v_mfma_f32_16x16x32_bf16 v[54:57], v[174:177], v[190:193], v[54:57]
	v_mfma_f32_16x16x32_bf16 v[46:49], v[182:185], v[190:193], v[46:49]
	v_mfma_f32_16x16x32_bf16 v[38:41], v[174:177], v[198:201], v[38:41]
	v_mfma_f32_16x16x32_bf16 v[30:33], v[182:185], v[198:201], v[30:33]
	v_mfma_f32_16x16x32_bf16 v[22:25], v[174:177], v[206:209], v[22:25]
	v_mfma_f32_16x16x32_bf16 v[14:17], v[182:185], v[206:209], v[14:17]
	v_mfma_f32_16x16x32_bf16 v[6:9], v[174:177], v[214:217], v[6:9]
	v_mfma_f32_16x16x32_bf16 v[2:5], v[182:185], v[214:217], v[2:5]
	s_setprio 0
	s_barrier
; #define PG8_STAGE(bufoff, gbase, voff) do { _Pragma("unroll") for (int _i = 0; _i < 2; ++_i) \
;         __builtin_amdgcn_global_load_lds((const unsigned*)((const char*)(gbase) + (voff)[_i]), (PG8_LAS unsigned*)(lds + (bufoff) + ldsw + _i * 8192), 16, 0, 0); } while (0)
; #define PG8_LDA(dst, b, h) do { _Pragma("unroll") for (int m = 0; m < 4; ++m) _Pragma("unroll") for (int k = 0; k < 2; ++k) dst[m][k] = *(const PG8_LAS bf16x8*)(lds + PG8_SA(b, h) + aoff + m * 2048 + k * 1024); } while (0)
; #define PG8_LDB(dst, b, h) do { _Pragma("unroll") for (int n = 0; n < 2; ++n) _Pragma("unroll") for (int k = 0; k < 2; ++k) dst[n][k] = *(const PG8_LAS bf16x8*)(lds + PG8_SB(b, h) + boff + n * 2048 + k * 1024); } while (0)
; #define PG8_MMA(ai, bj, At, Bt) do { __builtin_amdgcn_s_setprio(1); _Pragma("unroll") for (int m = 0; m < 4; ++m) _Pragma("unroll") for (int n = 0; n < 2; ++n) _Pragma("unroll") for (int k = 0; k < 2; ++k) \
;         acc[ai][bj][m][n] = __builtin_amdgcn_mfma_f32_16x16x32_bf16(Bt[n][k], At[m][k], acc[ai][bj][m][n], 0, 0, 0); __builtin_amdgcn_s_setprio(0); } while (0)
; #define PG8_WAIT_V(n) asm volatile("s_waitcnt vmcnt(" #n ")" ::: "memory")
; #define PG8_WAIT_L(n) asm volatile("s_waitcnt lgkmcnt(" #n ")" ::: "memory")
; #define PG8_BAR __builtin_amdgcn_s_barrier()
; #define PG8_SCHED __builtin_amdgcn_sched_barrier(0)
; template <class Epi, class Sched, bool ALIGN_EPI = false, bool SP2 = false>
; __device__ __forceinline__ void gemm_phase(PG8_LAS unsigned char* lds, const Gemm g, const Sched& S, const Epi& E) {
;     ...
;             PG8_LDB(B0, 1, 0); PG8_LDB(B1, 1, 1); PG8_SCHED; PG8_LDA(At, 1, 0); PG8_STAGE(PG8_SA(0, 1), a2 + hstep, voffA);
;             PG8_WAIT_V(8); PG8_WAIT_L(0); PG8_BAR; PG8_MMA(0, 0, At, B0); PG8_MMA(0, 1, At, B1); PG8_BAR; PG8_SCHED;
;             PG8_LDA(At, 1, 1); PG8_STAGE(PG8_SB(1, 0), b3, voffB); PG8_STAGE(PG8_SB(1, 1), b3 + hstep, voffB); PG8_STAGE(PG8_SA(1, 0), a3, voffA);
;             PG8_WAIT_V(8); PG8_WAIT_L(0); PG8_BAR; PG8_MMA(1, 0, At, B0); PG8_MMA(1, 1, At, B1); PG8_BAR; PG8_SCHED;
	s_add_i32 s79, 0, 0x18000
	v_add_u32_e32 v153, s79, v148
	s_add_i32 s80, 0, 0x1c000
	ds_read_b128 v[154:157], v153
	ds_read_b128 v[158:161], v153 offset:1024
	ds_read_b128 v[162:165], v153 offset:2048
	ds_read_b128 v[166:169], v153 offset:3072
	v_add_u32_e32 v153, s80, v148
	ds_read_b128 v[170:173], v153
	ds_read_b128 v[174:177], v153 offset:1024
	ds_read_b128 v[178:181], v153 offset:2048
	ds_read_b128 v[182:185], v153 offset:3072
	s_add_u32 s4, s50, 0x80000
	s_addc_u32 s5, s51, 0
	s_mov_b32 m0, s60
	ds_read_b128 v[186:189], v152 offset:32768
	ds_read_b128 v[190:193], v152 offset:33792
	ds_read_b128 v[194:197], v152 offset:34816
	ds_read_b128 v[198:201], v152 offset:35840
	ds_read_b128 v[202:205], v152 offset:36864
	ds_read_b128 v[206:209], v152 offset:37888
	ds_read_b128 v[210:213], v152 offset:38912
	ds_read_b128 v[214:217], v152 offset:39936
	global_load_lds_dwordx4 v130, s[4:5]
	s_mov_b32 m0, s61
	s_nop 0
	global_load_lds_dwordx4 v134, s[4:5]
	s_waitcnt vmcnt(8)
	s_waitcnt lgkmcnt(0)
	s_barrier
	s_setprio 1
	s_waitcnt lgkmcnt(0)
	v_mfma_f32_16x16x32_bf16 v[126:129], v[154:157], v[186:189], v[126:129]
	v_mfma_f32_16x16x32_bf16 v[122:125], v[162:165], v[186:189], v[122:125]
	v_mfma_f32_16x16x32_bf16 v[114:117], v[154:157], v[194:197], v[114:117]
	v_mfma_f32_16x16x32_bf16 v[106:109], v[162:165], v[194:197], v[106:109]
	v_mfma_f32_16x16x32_bf16 v[98:101], v[154:157], v[202:205], v[98:101]
	v_mfma_f32_16x16x32_bf16 v[90:93], v[162:165], v[202:205], v[90:93]
	v_mfma_f32_16x16x32_bf16 v[82:85], v[154:157], v[210:213], v[82:85]
	v_mfma_f32_16x16x32_bf16 v[74:77], v[162:165], v[210:213], v[74:77]
	v_mfma_f32_16x16x32_bf16 v[126:129], v[158:161], v[190:193], v[126:129]
	v_mfma_f32_16x16x32_bf16 v[122:125], v[166:169], v[190:193], v[122:125]
	v_mfma_f32_16x16x32_bf16 v[114:117], v[158:161], v[198:201], v[114:117]
	v_mfma_f32_16x16x32_bf16 v[106:109], v[166:169], v[198:201], v[106:109]
	v_mfma_f32_16x16x32_bf16 v[98:101], v[158:161], v[206:209], v[98:101]
	v_mfma_f32_16x16x32_bf16 v[90:93], v[166:169], v[206:209], v[90:93]
	v_mfma_f32_16x16x32_bf16 v[82:85], v[158:161], v[214:217], v[82:85]
	v_mfma_f32_16x16x32_bf16 v[74:77], v[166:169], v[214:217], v[74:77]
	s_setprio 0
	s_setprio 1
	v_mfma_f32_16x16x32_bf16 v[118:121], v[170:173], v[186:189], v[118:121]
	v_mfma_f32_16x16x32_bf16 v[110:113], v[178:181], v[186:189], v[110:113]
	v_mfma_f32_16x16x32_bf16 v[102:105], v[170:173], v[194:197], v[102:105]
	v_mfma_f32_16x16x32_bf16 v[94:97], v[178:181], v[194:197], v[94:97]
	v_mfma_f32_16x16x32_bf16 v[86:89], v[170:173], v[202:205], v[86:89]
	v_mfma_f32_16x16x32_bf16 v[78:81], v[178:181], v[202:205], v[78:81]
	v_mfma_f32_16x16x32_bf16 v[70:73], v[170:173], v[210:213], v[70:73]
	v_mfma_f32_16x16x32_bf16 v[66:69], v[178:181], v[210:213], v[66:69]
	v_mfma_f32_16x16x32_bf16 v[118:121], v[174:177], v[190:193], v[118:121]
	v_mfma_f32_16x16x32_bf16 v[110:113], v[182:185], v[190:193], v[110:113]
	v_mfma_f32_16x16x32_bf16 v[102:105], v[174:177], v[198:201], v[102:105]
	v_mfma_f32_16x16x32_bf16 v[94:97], v[182:185], v[198:201], v[94:97]
	v_mfma_f32_16x16x32_bf16 v[86:89], v[174:177], v[206:209], v[86:89]
	v_mfma_f32_16x16x32_bf16 v[78:81], v[182:185], v[206:209], v[78:81]
	v_mfma_f32_16x16x32_bf16 v[70:73], v[174:177], v[214:217], v[70:73]
	v_mfma_f32_16x16x32_bf16 v[66:69], v[182:185], v[214:217], v[66:69]
	s_setprio 0
	s_barrier
	s_add_i32 s4, s79, s58
	s_add_i32 m0, s4, 0xffffff80
	ds_read_b128 v[186:189], v152 offset:49152
	ds_read_b128 v[190:193], v152 offset:50176
	ds_read_b128 v[194:197], v152 offset:51200
	ds_read_b128 v[198:201], v152 offset:52224
	ds_read_b128 v[202:205], v152 offset:53248
	ds_read_b128 v[206:209], v152 offset:54272
	ds_read_b128 v[210:213], v152 offset:55296
	ds_read_b128 v[214:217], v152 offset:56320
	global_load_lds_dwordx4 v132, s[48:49] offset:128
	s_add_i32 m0, s4, 0x1f80
	s_add_u32 s4, s48, 0x80080
	s_addc_u32 s5, s49, 0
	global_load_lds_dwordx4 v136, s[48:49] offset:128
	s_add_i32 s48, s80, s58
	s_mov_b32 m0, s48
	s_nop 0
	global_load_lds_dwordx4 v132, s[4:5]
	s_add_i32 m0, s48, 0x2000
	s_nop 0
	global_load_lds_dwordx4 v136, s[4:5]
	s_add_i32 m0, s63, 0xffffff80
	s_nop 0
	global_load_lds_dwordx4 v130, s[50:51] offset:128
	s_add_i32 m0, s64, 0xffffff80
	s_nop 0
	global_load_lds_dwordx4 v134, s[50:51] offset:128
	s_waitcnt vmcnt(8)
	s_waitcnt lgkmcnt(0)
	s_barrier
	s_setprio 1
	s_waitcnt lgkmcnt(0)
	v_mfma_f32_16x16x32_bf16 v[62:65], v[154:157], v[186:189], v[62:65]
	v_mfma_f32_16x16x32_bf16 v[58:61], v[162:165], v[186:189], v[58:61]
	v_mfma_f32_16x16x32_bf16 v[50:53], v[154:157], v[194:197], v[50:53]
	v_mfma_f32_16x16x32_bf16 v[42:45], v[162:165], v[194:197], v[42:45]
	v_mfma_f32_16x16x32_bf16 v[34:37], v[154:157], v[202:205], v[34:37]
	v_mfma_f32_16x16x32_bf16 v[26:29], v[162:165], v[202:205], v[26:29]
	v_mfma_f32_16x16x32_bf16 v[18:21], v[154:157], v[210:213], v[18:21]
	v_mfma_f32_16x16x32_bf16 v[10:13], v[162:165], v[210:213], v[10:13]
	v_mfma_f32_16x16x32_bf16 v[62:65], v[158:161], v[190:193], v[62:65]
	v_mfma_f32_16x16x32_bf16 v[58:61], v[166:169], v[190:193], v[58:61]
	v_mfma_f32_16x16x32_bf16 v[50:53], v[158:161], v[198:201], v[50:53]
	v_mfma_f32_16x16x32_bf16 v[42:45], v[166:169], v[198:201], v[42:45]
	v_mfma_f32_16x16x32_bf16 v[34:37], v[158:161], v[206:209], v[34:37]
	v_mfma_f32_16x16x32_bf16 v[26:29], v[166:169], v[206:209], v[26:29]
	v_mfma_f32_16x16x32_bf16 v[18:21], v[158:161], v[214:217], v[18:21]
	v_mfma_f32_16x16x32_bf16 v[10:13], v[166:169], v[214:217], v[10:13]
	s_setprio 0
	s_setprio 1
	v_mfma_f32_16x16x32_bf16 v[54:57], v[170:173], v[186:189], v[54:57]
	v_mfma_f32_16x16x32_bf16 v[46:49], v[178:181], v[186:189], v[46:49]
	v_mfma_f32_16x16x32_bf16 v[38:41], v[170:173], v[194:197], v[38:41]
	v_mfma_f32_16x16x32_bf16 v[30:33], v[178:181], v[194:197], v[30:33]
	v_mfma_f32_16x16x32_bf16 v[22:25], v[170:173], v[202:205], v[22:25]
	v_mfma_f32_16x16x32_bf16 v[14:17], v[178:181], v[202:205], v[14:17]
	v_mfma_f32_16x16x32_bf16 v[6:9], v[170:173], v[210:213], v[6:9]
	v_mfma_f32_16x16x32_bf16 v[2:5], v[178:181], v[210:213], v[2:5]
	v_mfma_f32_16x16x32_bf16 v[54:57], v[174:177], v[190:193], v[54:57]
	v_mfma_f32_16x16x32_bf16 v[46:49], v[182:185], v[190:193], v[46:49]
	v_mfma_f32_16x16x32_bf16 v[38:41], v[174:177], v[198:201], v[38:41]
	v_mfma_f32_16x16x32_bf16 v[30:33], v[182:185], v[198:201], v[30:33]
	v_mfma_f32_16x16x32_bf16 v[22:25], v[174:177], v[206:209], v[22:25]
	v_mfma_f32_16x16x32_bf16 v[14:17], v[182:185], v[206:209], v[14:17]
	v_mfma_f32_16x16x32_bf16 v[6:9], v[174:177], v[214:217], v[6:9]
	v_mfma_f32_16x16x32_bf16 v[2:5], v[182:185], v[214:217], v[2:5]
	s_setprio 0
	s_barrier
	s_add_i32 s78, s78, 2
	s_add_u32 s40, s40, 0x100
	s_addc_u32 s41, s41, 0
	s_add_u32 s76, s76, 0x100
	s_addc_u32 s77, s77, 0
	s_cmp_gt_u32 s78, 29
	s_cbranch_scc0 .LBB0_763
	s_and_b64 vcc, exec, s[20:21]
	s_cbranch_vccz .LBB0_766
	s_barrier

; #define PG8_STAGE(bufoff, gbase, voff) do { _Pragma("unroll") for (int _i = 0; _i < 2; ++_i) \
;         __builtin_amdgcn_global_load_lds((const unsigned*)((const char*)(gbase) + (voff)[_i]), (PG8_LAS unsigned*)(lds + (bufoff) + ldsw + _i * 8192), 16, 0, 0); } while (0)
; #define PG8_LDA(dst, b, h) do { _Pragma("unroll") for (int m = 0; m < 4; ++m) _Pragma("unroll") for (int k = 0; k < 2; ++k) dst[m][k] = *(const PG8_LAS bf16x8*)(lds + PG8_SA(b, h) + aoff + m * 2048 + k * 1024); } while (0)
; #define PG8_LDB(dst, b, h) do { _Pragma("unroll") for (int n = 0; n < 2; ++n) _Pragma("unroll") for (int k = 0; k < 2; ++k) dst[n][k] = *(const PG8_LAS bf16x8*)(lds + PG8_SB(b, h) + boff + n * 2048 + k * 1024); } while (0)
; #define PG8_MMA(ai, bj, At, Bt) do { __builtin_amdgcn_s_setprio(1); _Pragma("unroll") for (int m = 0; m < 4; ++m) _Pragma("unroll") for (int n = 0; n < 2; ++n) _Pragma("unroll") for (int k = 0; k < 2; ++k) \
;         acc[ai][bj][m][n] = __builtin_amdgcn_mfma_f32_16x16x32_bf16(Bt[n][k], At[m][k], acc[ai][bj][m][n], 0, 0, 0); __builtin_amdgcn_s_setprio(0); } while (0)
; #define PG8_WAIT_V(n) asm volatile("s_waitcnt vmcnt(" #n ")" ::: "memory")
; #define PG8_WAIT_L(n) asm volatile("s_waitcnt lgkmcnt(" #n ")" ::: "memory")
; template <class Epi, class Sched, bool ALIGN_EPI = false, bool SP2 = false>
; __device__ __forceinline__ void gemm_phase(PG8_LAS unsigned char* lds, const Gemm g, const Sched& S, const Epi& E) {
;     ...
;             const bool last = (t == nt - 2);
;             const char* a1 = cA + (size_t)(t + 1) * kstep;
;             const char* a2 = last ? nA : cA + (size_t)(t + 2) * kstep; const char* b2 = last ? nB : cB + (size_t)(t + 2) * kstep;
;             const char* a3 = a2 + kstep; const char* b3 = b2 + kstep;
;             if (last && has_next) S.a_ready(nxt);
;             if constexpr (SP2) {
;             PG8_LDB(B0, 0, 0); PG8_LDB(B1, 0, 1); PG8_SCHED; PG8_LDA(At, 0, 0); PG8_STAGE(PG8_SA(1, 1), a1 + hstep, voffA);
;             PG8_WAIT_V(8); PG8_WAIT_L(0); PG8_BAR; PG8_MMA(0, 0, At, B0); PG8_MMA(0, 1, At, B1); PG8_BAR; PG8_SCHED;
;             PG8_LDA(At, 0, 1); PG8_STAGE(PG8_SB(0, 0), b2, voffB); PG8_STAGE(PG8_SB(0, 1), b2 + hstep, voffB); PG8_STAGE(PG8_SA(0, 0), a2, voffA);
;             PG8_WAIT_V(8); PG8_WAIT_L(0); PG8_BAR; PG8_MMA(1, 0, At, B0); PG8_MMA(1, 1, At, B1); PG8_BAR; PG8_SCHED;
.LBB0_913:
	ds_read_b128 v[156:159], v152
	ds_read_b128 v[160:163], v152 offset:1024
	ds_read_b128 v[164:167], v152 offset:2048
	ds_read_b128 v[168:171], v152 offset:3072
	ds_read_b128 v[172:175], v153
	ds_read_b128 v[176:179], v153 offset:1024
	ds_read_b128 v[180:183], v153 offset:2048
	ds_read_b128 v[184:187], v153 offset:3072
	s_add_u32 s4, s34, 0xfff80080
	s_addc_u32 s5, s35, -1
	s_cmp_eq_u32 s69, 28
	s_cselect_b32 s39, s25, s5
	s_cselect_b32 s38, s65, s4
	s_cselect_b32 s37, s23, s68
	s_cselect_b32 s36, s66, s67
	s_add_i32 m0, s31, 0xc000
	ds_read_b128 v[188:191], v154
	ds_read_b128 v[192:195], v154 offset:1024
	ds_read_b128 v[196:199], v154 offset:2048
	ds_read_b128 v[200:203], v154 offset:3072
	ds_read_b128 v[204:207], v154 offset:4096
	ds_read_b128 v[208:211], v154 offset:5120
	ds_read_b128 v[212:215], v154 offset:6144
	ds_read_b128 v[216:219], v154 offset:7168
	global_load_lds_dwordx4 v138, s[34:35]
	s_add_i32 m0, s31, 0xe000
	s_nop 0
	global_load_lds_dwordx4 v140, s[34:35]
	s_waitcnt vmcnt(8)
	s_waitcnt lgkmcnt(0)
	s_barrier
	s_setprio 1
	s_waitcnt lgkmcnt(0)
	v_mfma_f32_16x16x32_bf16 v[126:129], v[156:159], v[188:191], v[126:129]
	v_mfma_f32_16x16x32_bf16 v[122:125], v[164:167], v[188:191], v[122:125]
	v_mfma_f32_16x16x32_bf16 v[110:113], v[156:159], v[196:199], v[110:113]
	v_mfma_f32_16x16x32_bf16 v[106:109], v[164:167], v[196:199], v[106:109]
	v_mfma_f32_16x16x32_bf16 v[94:97], v[156:159], v[204:207], v[94:97]
	v_mfma_f32_16x16x32_bf16 v[90:93], v[164:167], v[204:207], v[90:93]
	v_mfma_f32_16x16x32_bf16 v[78:81], v[156:159], v[212:215], v[78:81]
	v_mfma_f32_16x16x32_bf16 v[74:77], v[164:167], v[212:215], v[74:77]
	v_mfma_f32_16x16x32_bf16 v[126:129], v[160:163], v[192:195], v[126:129]
	v_mfma_f32_16x16x32_bf16 v[122:125], v[168:171], v[192:195], v[122:125]
	v_mfma_f32_16x16x32_bf16 v[110:113], v[160:163], v[200:203], v[110:113]
	v_mfma_f32_16x16x32_bf16 v[106:109], v[168:171], v[200:203], v[106:109]
	v_mfma_f32_16x16x32_bf16 v[94:97], v[160:163], v[208:211], v[94:97]
	v_mfma_f32_16x16x32_bf16 v[90:93], v[168:171], v[208:211], v[90:93]
	v_mfma_f32_16x16x32_bf16 v[78:81], v[160:163], v[216:219], v[78:81]
	v_mfma_f32_16x16x32_bf16 v[74:77], v[168:171], v[216:219], v[74:77]
	s_setprio 0
	s_setprio 1
	v_mfma_f32_16x16x32_bf16 v[118:121], v[172:175], v[188:191], v[118:121]
	v_mfma_f32_16x16x32_bf16 v[114:117], v[180:183], v[188:191], v[114:117]
	v_mfma_f32_16x16x32_bf16 v[102:105], v[172:175], v[196:199], v[102:105]
	v_mfma_f32_16x16x32_bf16 v[98:101], v[180:183], v[196:199], v[98:101]
	v_mfma_f32_16x16x32_bf16 v[86:89], v[172:175], v[204:207], v[86:89]
	v_mfma_f32_16x16x32_bf16 v[82:85], v[180:183], v[204:207], v[82:85]
	v_mfma_f32_16x16x32_bf16 v[70:73], v[172:175], v[212:215], v[70:73]
	v_mfma_f32_16x16x32_bf16 v[66:69], v[180:183], v[212:215], v[66:69]
	v_mfma_f32_16x16x32_bf16 v[118:121], v[176:179], v[192:195], v[118:121]
	v_mfma_f32_16x16x32_bf16 v[114:117], v[184:187], v[192:195], v[114:117]
	v_mfma_f32_16x16x32_bf16 v[102:105], v[176:179], v[200:203], v[102:105]
	v_mfma_f32_16x16x32_bf16 v[98:101], v[184:187], v[200:203], v[98:101]
	v_mfma_f32_16x16x32_bf16 v[86:89], v[176:179], v[208:211], v[86:89]
	v_mfma_f32_16x16x32_bf16 v[82:85], v[184:187], v[208:211], v[82:85]
	v_mfma_f32_16x16x32_bf16 v[70:73], v[176:179], v[216:219], v[70:73]
	v_mfma_f32_16x16x32_bf16 v[66:69], v[184:187], v[216:219], v[66:69]
	s_setprio 0
	s_barrier
	s_add_i32 s4, s61, s40
	s_mov_b32 m0, s4
	ds_read_b128 v[188:191], v154 offset:16384
	ds_read_b128 v[192:195], v154 offset:17408
	ds_read_b128 v[196:199], v154 offset:18432
	ds_read_b128 v[200:203], v154 offset:19456
	ds_read_b128 v[204:207], v154 offset:20480
	ds_read_b128 v[208:211], v154 offset:21504
	ds_read_b128 v[212:215], v154 offset:22528
	ds_read_b128 v[216:219], v154 offset:23552
	global_load_lds_dwordx4 v134, s[36:37]
	s_add_i32 m0, s4, 0x2000
	s_add_u32 s4, s36, 0x80000
	s_addc_u32 s5, s37, 0
	s_add_i32 s70, s62, s40
	global_load_lds_dwordx4 v130, s[36:37]
	s_mov_b32 m0, s70
	s_nop 0
	global_load_lds_dwordx4 v134, s[4:5]
	s_add_i32 m0, s70, 0x2000
	s_nop 0
	global_load_lds_dwordx4 v130, s[4:5]
	s_mov_b32 m0, s31
	s_nop 0
	global_load_lds_dwordx4 v136, s[38:39]
	s_mov_b32 m0, s49
	s_nop 0
	global_load_lds_dwordx4 v132, s[38:39]
	s_waitcnt vmcnt(8)
	s_waitcnt lgkmcnt(0)
	s_barrier
	s_setprio 1
	s_waitcnt lgkmcnt(0)
	v_mfma_f32_16x16x32_bf16 v[62:65], v[156:159], v[188:191], v[62:65]
	v_mfma_f32_16x16x32_bf16 v[58:61], v[164:167], v[188:191], v[58:61]
	v_mfma_f32_16x16x32_bf16 v[46:49], v[156:159], v[196:199], v[46:49]
	v_mfma_f32_16x16x32_bf16 v[42:45], v[164:167], v[196:199], v[42:45]
	v_mfma_f32_16x16x32_bf16 v[30:33], v[156:159], v[204:207], v[30:33]
	v_mfma_f32_16x16x32_bf16 v[26:29], v[164:167], v[204:207], v[26:29]
	v_mfma_f32_16x16x32_bf16 v[14:17], v[156:159], v[212:215], v[14:17]
	v_mfma_f32_16x16x32_bf16 v[10:13], v[164:167], v[212:215], v[10:13]
	v_mfma_f32_16x16x32_bf16 v[62:65], v[160:163], v[192:195], v[62:65]
	v_mfma_f32_16x16x32_bf16 v[58:61], v[168:171], v[192:195], v[58:61]
	v_mfma_f32_16x16x32_bf16 v[46:49], v[160:163], v[200:203], v[46:49]
	v_mfma_f32_16x16x32_bf16 v[42:45], v[168:171], v[200:203], v[42:45]
	v_mfma_f32_16x16x32_bf16 v[30:33], v[160:163], v[208:211], v[30:33]
	v_mfma_f32_16x16x32_bf16 v[26:29], v[168:171], v[208:211], v[26:29]
	v_mfma_f32_16x16x32_bf16 v[14:17], v[160:163], v[216:219], v[14:17]
	v_mfma_f32_16x16x32_bf16 v[10:13], v[168:171], v[216:219], v[10:13]
	s_setprio 0
	s_setprio 1
	v_mfma_f32_16x16x32_bf16 v[54:57], v[172:175], v[188:191], v[54:57]
	v_mfma_f32_16x16x32_bf16 v[50:53], v[180:183], v[188:191], v[50:53]
	v_mfma_f32_16x16x32_bf16 v[38:41], v[172:175], v[196:199], v[38:41]
	v_mfma_f32_16x16x32_bf16 v[34:37], v[180:183], v[196:199], v[34:37]
	v_mfma_f32_16x16x32_bf16 v[22:25], v[172:175], v[204:207], v[22:25]
	v_mfma_f32_16x16x32_bf16 v[18:21], v[180:183], v[204:207], v[18:21]
	v_mfma_f32_16x16x32_bf16 v[6:9], v[172:175], v[212:215], v[6:9]
	v_mfma_f32_16x16x32_bf16 v[2:5], v[180:183], v[212:215], v[2:5]
	v_mfma_f32_16x16x32_bf16 v[54:57], v[176:179], v[192:195], v[54:57]
	v_mfma_f32_16x16x32_bf16 v[50:53], v[184:187], v[192:195], v[50:53]
	v_mfma_f32_16x16x32_bf16 v[38:41], v[176:179], v[200:203], v[38:41]
	v_mfma_f32_16x16x32_bf16 v[34:37], v[184:187], v[200:203], v[34:37]
	v_mfma_f32_16x16x32_bf16 v[22:25], v[176:179], v[208:211], v[22:25]
	v_mfma_f32_16x16x32_bf16 v[18:21], v[184:187], v[208:211], v[18:21]
	v_mfma_f32_16x16x32_bf16 v[6:9], v[176:179], v[216:219], v[6:9]
	v_mfma_f32_16x16x32_bf16 v[2:5], v[184:187], v[216:219], v[2:5]
	s_setprio 0
	s_barrier
; #define PG8_STAGE(bufoff, gbase, voff) do { _Pragma("unroll") for (int _i = 0; _i < 2; ++_i) \
;         __builtin_amdgcn_global_load_lds((const unsigned*)((const char*)(gbase) + (voff)[_i]), (PG8_LAS unsigned*)(lds + (bufoff) + ldsw + _i * 8192), 16, 0, 0); } while (0)
; #define PG8_LDA(dst, b, h) do { _Pragma("unroll") for (int m = 0; m < 4; ++m) _Pragma("unroll") for (int k = 0; k < 2; ++k) dst[m][k] = *(const PG8_LAS bf16x8*)(lds + PG8_SA(b, h) + aoff + m * 2048 + k * 1024); } while (0)
; #define PG8_LDB(dst, b, h) do { _Pragma("unroll") for (int n = 0; n < 2; ++n) _Pragma("unroll") for (int k = 0; k < 2; ++k) dst[n][k] = *(const PG8_LAS bf16x8*)(lds + PG8_SB(b, h) + boff + n * 2048 + k * 1024); } while (0)
; #define PG8_MMA(ai, bj, At, Bt) do { __builtin_amdgcn_s_setprio(1); _Pragma("unroll") for (int m = 0; m < 4; ++m) _Pragma("unroll") for (int n = 0; n < 2; ++n) _Pragma("unroll") for (int k = 0; k < 2; ++k) \
;         acc[ai][bj][m][n] = __builtin_amdgcn_mfma_f32_16x16x32_bf16(Bt[n][k], At[m][k], acc[ai][bj][m][n], 0, 0, 0); __builtin_amdgcn_s_setprio(0); } while (0)
; #define PG8_WAIT_V(n) asm volatile("s_waitcnt vmcnt(" #n ")" ::: "memory")
; #define PG8_WAIT_L(n) asm volatile("s_waitcnt lgkmcnt(" #n ")" ::: "memory")
; #define PG8_BAR __builtin_amdgcn_s_barrier()
; #define PG8_SCHED __builtin_amdgcn_sched_barrier(0)
; template <class Epi, class Sched, bool ALIGN_EPI = false, bool SP2 = false>
; __device__ __forceinline__ void gemm_phase(PG8_LAS unsigned char* lds, const Gemm g, const Sched& S, const Epi& E) {
;     ...
;             PG8_LDB(B0, 1, 0); PG8_LDB(B1, 1, 1); PG8_SCHED; PG8_LDA(At, 1, 0); PG8_STAGE(PG8_SA(0, 1), a2 + hstep, voffA);
;             PG8_WAIT_V(8); PG8_WAIT_L(0); PG8_BAR; PG8_MMA(0, 0, At, B0); PG8_MMA(0, 1, At, B1); PG8_BAR; PG8_SCHED;
;             PG8_LDA(At, 1, 1); PG8_STAGE(PG8_SB(1, 0), b3, voffB); PG8_STAGE(PG8_SB(1, 1), b3 + hstep, voffB); PG8_STAGE(PG8_SA(1, 0), a3, voffA);
;             PG8_WAIT_V(8); PG8_WAIT_L(0); PG8_BAR; PG8_MMA(1, 0, At, B0); PG8_MMA(1, 1, At, B1); PG8_BAR; PG8_SCHED;
	s_add_i32 s70, 0, 0x18000
	v_add_u32_e32 v155, s70, v150
	s_add_i32 s71, 0, 0x1c000
	ds_read_b128 v[156:159], v155
	ds_read_b128 v[160:163], v155 offset:1024
	ds_read_b128 v[164:167], v155 offset:2048
	ds_read_b128 v[168:171], v155 offset:3072
	v_add_u32_e32 v155, s71, v150
	ds_read_b128 v[172:175], v155
	ds_read_b128 v[176:179], v155 offset:1024
	ds_read_b128 v[180:183], v155 offset:2048
	ds_read_b128 v[184:187], v155 offset:3072
	s_add_u32 s4, s38, 0x80000
	s_addc_u32 s5, s39, 0
	s_mov_b32 m0, s50
	ds_read_b128 v[188:191], v154 offset:32768
	ds_read_b128 v[192:195], v154 offset:33792
	ds_read_b128 v[196:199], v154 offset:34816
	ds_read_b128 v[200:203], v154 offset:35840
	ds_read_b128 v[204:207], v154 offset:36864
	ds_read_b128 v[208:211], v154 offset:37888
	ds_read_b128 v[212:215], v154 offset:38912
	ds_read_b128 v[216:219], v154 offset:39936
	global_load_lds_dwordx4 v136, s[4:5]
	s_mov_b32 m0, s51
	s_nop 0
	global_load_lds_dwordx4 v132, s[4:5]
	s_waitcnt vmcnt(8)
	s_waitcnt lgkmcnt(0)
	s_barrier
	s_setprio 1
	s_waitcnt lgkmcnt(0)
	v_mfma_f32_16x16x32_bf16 v[126:129], v[156:159], v[188:191], v[126:129]
	v_mfma_f32_16x16x32_bf16 v[122:125], v[164:167], v[188:191], v[122:125]
	v_mfma_f32_16x16x32_bf16 v[110:113], v[156:159], v[196:199], v[110:113]
	v_mfma_f32_16x16x32_bf16 v[106:109], v[164:167], v[196:199], v[106:109]
	v_mfma_f32_16x16x32_bf16 v[94:97], v[156:159], v[204:207], v[94:97]
	v_mfma_f32_16x16x32_bf16 v[90:93], v[164:167], v[204:207], v[90:93]
	v_mfma_f32_16x16x32_bf16 v[78:81], v[156:159], v[212:215], v[78:81]
	v_mfma_f32_16x16x32_bf16 v[74:77], v[164:167], v[212:215], v[74:77]
	v_mfma_f32_16x16x32_bf16 v[126:129], v[160:163], v[192:195], v[126:129]
	v_mfma_f32_16x16x32_bf16 v[122:125], v[168:171], v[192:195], v[122:125]
	v_mfma_f32_16x16x32_bf16 v[110:113], v[160:163], v[200:203], v[110:113]
	v_mfma_f32_16x16x32_bf16 v[106:109], v[168:171], v[200:203], v[106:109]
	v_mfma_f32_16x16x32_bf16 v[94:97], v[160:163], v[208:211], v[94:97]
	v_mfma_f32_16x16x32_bf16 v[90:93], v[168:171], v[208:211], v[90:93]
	v_mfma_f32_16x16x32_bf16 v[78:81], v[160:163], v[216:219], v[78:81]
	v_mfma_f32_16x16x32_bf16 v[74:77], v[168:171], v[216:219], v[74:77]
	s_setprio 0
	s_setprio 1
	v_mfma_f32_16x16x32_bf16 v[118:121], v[172:175], v[188:191], v[118:121]
	v_mfma_f32_16x16x32_bf16 v[114:117], v[180:183], v[188:191], v[114:117]
	v_mfma_f32_16x16x32_bf16 v[102:105], v[172:175], v[196:199], v[102:105]
	v_mfma_f32_16x16x32_bf16 v[98:101], v[180:183], v[196:199], v[98:101]
	v_mfma_f32_16x16x32_bf16 v[86:89], v[172:175], v[204:207], v[86:89]
	v_mfma_f32_16x16x32_bf16 v[82:85], v[180:183], v[204:207], v[82:85]
	v_mfma_f32_16x16x32_bf16 v[70:73], v[172:175], v[212:215], v[70:73]
	v_mfma_f32_16x16x32_bf16 v[66:69], v[180:183], v[212:215], v[66:69]
	v_mfma_f32_16x16x32_bf16 v[118:121], v[176:179], v[192:195], v[118:121]
	v_mfma_f32_16x16x32_bf16 v[114:117], v[184:187], v[192:195], v[114:117]
	v_mfma_f32_16x16x32_bf16 v[102:105], v[176:179], v[200:203], v[102:105]
	v_mfma_f32_16x16x32_bf16 v[98:101], v[184:187], v[200:203], v[98:101]
	v_mfma_f32_16x16x32_bf16 v[86:89], v[176:179], v[208:211], v[86:89]
	v_mfma_f32_16x16x32_bf16 v[82:85], v[184:187], v[208:211], v[82:85]
	v_mfma_f32_16x16x32_bf16 v[70:73], v[176:179], v[216:219], v[70:73]
	v_mfma_f32_16x16x32_bf16 v[66:69], v[184:187], v[216:219], v[66:69]
	s_setprio 0
	s_barrier
	s_add_i32 s4, s70, s40
	s_add_i32 m0, s4, 0xffffff80
	ds_read_b128 v[188:191], v154 offset:49152
	ds_read_b128 v[192:195], v154 offset:50176
	ds_read_b128 v[196:199], v154 offset:51200
	ds_read_b128 v[200:203], v154 offset:52224
	ds_read_b128 v[204:207], v154 offset:53248
	ds_read_b128 v[208:211], v154 offset:54272
	ds_read_b128 v[212:215], v154 offset:55296
	ds_read_b128 v[216:219], v154 offset:56320
	global_load_lds_dwordx4 v134, s[36:37] offset:128
	s_add_i32 m0, s4, 0x1f80
	s_add_u32 s4, s36, 0x80080
	s_addc_u32 s5, s37, 0
	global_load_lds_dwordx4 v130, s[36:37] offset:128
	s_add_i32 s36, s71, s40
	s_mov_b32 m0, s36
	s_nop 0
	global_load_lds_dwordx4 v134, s[4:5]
	s_add_i32 m0, s36, 0x2000
	s_nop 0
	global_load_lds_dwordx4 v130, s[4:5]
	s_add_i32 m0, s53, 0xffffff80
	s_nop 0
	global_load_lds_dwordx4 v136, s[38:39] offset:128
	s_add_i32 m0, s58, 0xffffff80
	s_nop 0
	global_load_lds_dwordx4 v132, s[38:39] offset:128
	s_waitcnt vmcnt(8)
	s_waitcnt lgkmcnt(0)
	s_barrier
	s_setprio 1
	s_waitcnt lgkmcnt(0)
	v_mfma_f32_16x16x32_bf16 v[62:65], v[156:159], v[188:191], v[62:65]
	v_mfma_f32_16x16x32_bf16 v[58:61], v[164:167], v[188:191], v[58:61]
	v_mfma_f32_16x16x32_bf16 v[46:49], v[156:159], v[196:199], v[46:49]
	v_mfma_f32_16x16x32_bf16 v[42:45], v[164:167], v[196:199], v[42:45]
	v_mfma_f32_16x16x32_bf16 v[30:33], v[156:159], v[204:207], v[30:33]
	v_mfma_f32_16x16x32_bf16 v[26:29], v[164:167], v[204:207], v[26:29]
	v_mfma_f32_16x16x32_bf16 v[14:17], v[156:159], v[212:215], v[14:17]
	v_mfma_f32_16x16x32_bf16 v[10:13], v[164:167], v[212:215], v[10:13]
	v_mfma_f32_16x16x32_bf16 v[62:65], v[160:163], v[192:195], v[62:65]
	v_mfma_f32_16x16x32_bf16 v[58:61], v[168:171], v[192:195], v[58:61]
	v_mfma_f32_16x16x32_bf16 v[46:49], v[160:163], v[200:203], v[46:49]
	v_mfma_f32_16x16x32_bf16 v[42:45], v[168:171], v[200:203], v[42:45]
	v_mfma_f32_16x16x32_bf16 v[30:33], v[160:163], v[208:211], v[30:33]
	v_mfma_f32_16x16x32_bf16 v[26:29], v[168:171], v[208:211], v[26:29]
	v_mfma_f32_16x16x32_bf16 v[14:17], v[160:163], v[216:219], v[14:17]
	v_mfma_f32_16x16x32_bf16 v[10:13], v[168:171], v[216:219], v[10:13]
	s_setprio 0
	s_setprio 1
	v_mfma_f32_16x16x32_bf16 v[54:57], v[172:175], v[188:191], v[54:57]
	v_mfma_f32_16x16x32_bf16 v[50:53], v[180:183], v[188:191], v[50:53]
	v_mfma_f32_16x16x32_bf16 v[38:41], v[172:175], v[196:199], v[38:41]
	v_mfma_f32_16x16x32_bf16 v[34:37], v[180:183], v[196:199], v[34:37]
	v_mfma_f32_16x16x32_bf16 v[22:25], v[172:175], v[204:207], v[22:25]
	v_mfma_f32_16x16x32_bf16 v[18:21], v[180:183], v[204:207], v[18:21]
	v_mfma_f32_16x16x32_bf16 v[6:9], v[172:175], v[212:215], v[6:9]
	v_mfma_f32_16x16x32_bf16 v[2:5], v[180:183], v[212:215], v[2:5]
	v_mfma_f32_16x16x32_bf16 v[54:57], v[176:179], v[192:195], v[54:57]
	v_mfma_f32_16x16x32_bf16 v[50:53], v[184:187], v[192:195], v[50:53]
	v_mfma_f32_16x16x32_bf16 v[38:41], v[176:179], v[200:203], v[38:41]
	v_mfma_f32_16x16x32_bf16 v[34:37], v[184:187], v[200:203], v[34:37]
	v_mfma_f32_16x16x32_bf16 v[22:25], v[176:179], v[208:211], v[22:25]
	v_mfma_f32_16x16x32_bf16 v[18:21], v[184:187], v[208:211], v[18:21]
	v_mfma_f32_16x16x32_bf16 v[6:9], v[176:179], v[216:219], v[6:9]
	v_mfma_f32_16x16x32_bf16 v[2:5], v[184:187], v[216:219], v[2:5]
	s_setprio 0
	s_barrier
	s_add_i32 s69, s69, 2
	s_add_u32 s34, s34, 0x100
	s_addc_u32 s35, s35, 0
	s_add_u32 s67, s67, 0x100
	s_addc_u32 s68, s68, 0
	s_cmp_gt_u32 s69, 29
	s_cbranch_scc0 .LBB0_913
	s_and_b64 vcc, exec, s[20:21]
	s_cbranch_vccz .LBB0_916
	s_barrier

; #define PG8_STAGE(bufoff, gbase, voff) do { _Pragma("unroll") for (int _i = 0; _i < 2; ++_i) \
;         __builtin_amdgcn_global_load_lds((const unsigned*)((const char*)(gbase) + (voff)[_i]), (PG8_LAS unsigned*)(lds + (bufoff) + ldsw + _i * 8192), 16, 0, 0); } while (0)
; #define PG8_LDA(dst, b, h) do { _Pragma("unroll") for (int m = 0; m < 4; ++m) _Pragma("unroll") for (int k = 0; k < 2; ++k) dst[m][k] = *(const PG8_LAS bf16x8*)(lds + PG8_SA(b, h) + aoff + m * 2048 + k * 1024); } while (0)
; #define PG8_LDB(dst, b, h) do { _Pragma("unroll") for (int n = 0; n < 2; ++n) _Pragma("unroll") for (int k = 0; k < 2; ++k) dst[n][k] = *(const PG8_LAS bf16x8*)(lds + PG8_SB(b, h) + boff + n * 2048 + k * 1024); } while (0)
; #define PG8_MMA(ai, bj, At, Bt) do { __builtin_amdgcn_s_setprio(1); _Pragma("unroll") for (int m = 0; m < 4; ++m) _Pragma("unroll") for (int n = 0; n < 2; ++n) _Pragma("unroll") for (int k = 0; k < 2; ++k) \
;         acc[ai][bj][m][n] = __builtin_amdgcn_mfma_f32_16x16x32_bf16(Bt[n][k], At[m][k], acc[ai][bj][m][n], 0, 0, 0); __builtin_amdgcn_s_setprio(0); } while (0)
; #define PG8_WAIT_V(n) asm volatile("s_waitcnt vmcnt(" #n ")" ::: "memory")
; #define PG8_WAIT_L(n) asm volatile("s_waitcnt lgkmcnt(" #n ")" ::: "memory")
; template <class Epi, class Sched, bool ALIGN_EPI = false, bool SP2 = false>
; __device__ __forceinline__ void gemm_phase(PG8_LAS unsigned char* lds, const Gemm g, const Sched& S, const Epi& E) {
;     ...
;             const bool last = (t == nt - 2);
;             const char* a1 = cA + (size_t)(t + 1) * kstep;
;             const char* a2 = last ? nA : cA + (size_t)(t + 2) * kstep; const char* b2 = last ? nB : cB + (size_t)(t + 2) * kstep;
;             const char* a3 = a2 + kstep; const char* b3 = b2 + kstep;
;             if (last && has_next) S.a_ready(nxt);
;             if constexpr (SP2) {
;             PG8_LDB(B0, 0, 0); PG8_LDB(B1, 0, 1); PG8_SCHED; PG8_LDA(At, 0, 0); PG8_STAGE(PG8_SA(1, 1), a1 + hstep, voffA);
;             PG8_WAIT_V(8); PG8_WAIT_L(0); PG8_BAR; PG8_MMA(0, 0, At, B0); PG8_MMA(0, 1, At, B1); PG8_BAR; PG8_SCHED;
;             PG8_LDA(At, 0, 1); PG8_STAGE(PG8_SB(0, 0), b2, voffB); PG8_STAGE(PG8_SB(0, 1), b2 + hstep, voffB); PG8_STAGE(PG8_SA(0, 0), a2, voffA);
;             PG8_WAIT_V(8); PG8_WAIT_L(0); PG8_BAR; PG8_MMA(1, 0, At, B0); PG8_MMA(1, 1, At, B1); PG8_BAR; PG8_SCHED;
.LBB0_1017:
	ds_read_b128 v[154:157], v150
	ds_read_b128 v[158:161], v150 offset:1024
	ds_read_b128 v[162:165], v150 offset:2048
	ds_read_b128 v[166:169], v150 offset:3072
	ds_read_b128 v[170:173], v151
	ds_read_b128 v[174:177], v151 offset:1024
	ds_read_b128 v[178:181], v151 offset:2048
	ds_read_b128 v[182:185], v151 offset:3072
	s_add_u32 s34, s30, 0x100
	s_addc_u32 s35, s31, 0
	s_cmpk_eq_i32 s74, 0x54
	s_cselect_b32 s39, s9, s35
	s_cselect_b32 s38, s8, s34
	s_cselect_b32 s37, s29, s73
	s_cselect_b32 s36, s28, s72
	s_add_i32 m0, s49, 0xc000
	ds_read_b128 v[186:189], v152
	ds_read_b128 v[190:193], v152 offset:1024
	ds_read_b128 v[194:197], v152 offset:2048
	ds_read_b128 v[198:201], v152 offset:3072
	ds_read_b128 v[202:205], v152 offset:4096
	ds_read_b128 v[206:209], v152 offset:5120
	ds_read_b128 v[210:213], v152 offset:6144
	ds_read_b128 v[214:217], v152 offset:7168
	global_load_lds_dwordx4 v138, s[30:31]
	s_add_i32 m0, s49, 0xe000
	s_nop 0
	global_load_lds_dwordx4 v140, s[30:31]
	s_waitcnt vmcnt(8)
	s_waitcnt lgkmcnt(0)
	s_barrier
	s_setprio 1
	s_waitcnt lgkmcnt(0)
	v_mfma_f32_16x16x32_bf16 v[126:129], v[154:157], v[186:189], v[126:129]
	v_mfma_f32_16x16x32_bf16 v[122:125], v[162:165], v[186:189], v[122:125]
	v_mfma_f32_16x16x32_bf16 v[114:117], v[154:157], v[194:197], v[114:117]
	v_mfma_f32_16x16x32_bf16 v[106:109], v[162:165], v[194:197], v[106:109]
	v_mfma_f32_16x16x32_bf16 v[98:101], v[154:157], v[202:205], v[98:101]
	v_mfma_f32_16x16x32_bf16 v[90:93], v[162:165], v[202:205], v[90:93]
	v_mfma_f32_16x16x32_bf16 v[82:85], v[154:157], v[210:213], v[82:85]
	v_mfma_f32_16x16x32_bf16 v[74:77], v[162:165], v[210:213], v[74:77]
	v_mfma_f32_16x16x32_bf16 v[126:129], v[158:161], v[190:193], v[126:129]
	v_mfma_f32_16x16x32_bf16 v[122:125], v[166:169], v[190:193], v[122:125]
	v_mfma_f32_16x16x32_bf16 v[114:117], v[158:161], v[198:201], v[114:117]
	v_mfma_f32_16x16x32_bf16 v[106:109], v[166:169], v[198:201], v[106:109]
	v_mfma_f32_16x16x32_bf16 v[98:101], v[158:161], v[206:209], v[98:101]
	v_mfma_f32_16x16x32_bf16 v[90:93], v[166:169], v[206:209], v[90:93]
	v_mfma_f32_16x16x32_bf16 v[82:85], v[158:161], v[214:217], v[82:85]
	v_mfma_f32_16x16x32_bf16 v[74:77], v[166:169], v[214:217], v[74:77]
	s_setprio 0
	s_setprio 1
	v_mfma_f32_16x16x32_bf16 v[118:121], v[170:173], v[186:189], v[118:121]
	v_mfma_f32_16x16x32_bf16 v[110:113], v[178:181], v[186:189], v[110:113]
	v_mfma_f32_16x16x32_bf16 v[102:105], v[170:173], v[194:197], v[102:105]
	v_mfma_f32_16x16x32_bf16 v[94:97], v[178:181], v[194:197], v[94:97]
	v_mfma_f32_16x16x32_bf16 v[86:89], v[170:173], v[202:205], v[86:89]
	v_mfma_f32_16x16x32_bf16 v[78:81], v[178:181], v[202:205], v[78:81]
	v_mfma_f32_16x16x32_bf16 v[70:73], v[170:173], v[210:213], v[70:73]
	v_mfma_f32_16x16x32_bf16 v[66:69], v[178:181], v[210:213], v[66:69]
	v_mfma_f32_16x16x32_bf16 v[118:121], v[174:177], v[190:193], v[118:121]
	v_mfma_f32_16x16x32_bf16 v[110:113], v[182:185], v[190:193], v[110:113]
	v_mfma_f32_16x16x32_bf16 v[102:105], v[174:177], v[198:201], v[102:105]
	v_mfma_f32_16x16x32_bf16 v[94:97], v[182:185], v[198:201], v[94:97]
	v_mfma_f32_16x16x32_bf16 v[86:89], v[174:177], v[206:209], v[86:89]
	v_mfma_f32_16x16x32_bf16 v[78:81], v[182:185], v[206:209], v[78:81]
	v_mfma_f32_16x16x32_bf16 v[70:73], v[174:177], v[214:217], v[70:73]
	v_mfma_f32_16x16x32_bf16 v[66:69], v[182:185], v[214:217], v[66:69]
	s_setprio 0
	s_barrier
	s_add_i32 s4, s62, s48
	s_mov_b32 m0, s4
	ds_read_b128 v[186:189], v152 offset:16384
	ds_read_b128 v[190:193], v152 offset:17408
	ds_read_b128 v[194:197], v152 offset:18432
	ds_read_b128 v[198:201], v152 offset:19456
	ds_read_b128 v[202:205], v152 offset:20480
	ds_read_b128 v[206:209], v152 offset:21504
	ds_read_b128 v[210:213], v152 offset:22528
	ds_read_b128 v[214:217], v152 offset:23552
	global_load_lds_dwordx4 v132, s[36:37]
	s_add_i32 m0, s4, 0x2000
	s_add_u32 s4, s36, 0x160000
	s_addc_u32 s5, s37, 0
	s_add_i32 s30, s63, s48
	global_load_lds_dwordx4 v136, s[36:37]
	s_mov_b32 m0, s30
	s_nop 0
	global_load_lds_dwordx4 v132, s[4:5]
	s_add_i32 m0, s30, 0x2000
	s_nop 0
	global_load_lds_dwordx4 v136, s[4:5]
	s_mov_b32 m0, s49
	s_nop 0
	global_load_lds_dwordx4 v130, s[38:39]
	s_mov_b32 m0, s50
	s_nop 0
	global_load_lds_dwordx4 v134, s[38:39]
	s_waitcnt vmcnt(8)
	s_waitcnt lgkmcnt(0)
	s_barrier
	s_setprio 1
	s_waitcnt lgkmcnt(0)
	v_mfma_f32_16x16x32_bf16 v[62:65], v[154:157], v[186:189], v[62:65]
	v_mfma_f32_16x16x32_bf16 v[58:61], v[162:165], v[186:189], v[58:61]
	v_mfma_f32_16x16x32_bf16 v[50:53], v[154:157], v[194:197], v[50:53]
	v_mfma_f32_16x16x32_bf16 v[42:45], v[162:165], v[194:197], v[42:45]
	v_mfma_f32_16x16x32_bf16 v[34:37], v[154:157], v[202:205], v[34:37]
	v_mfma_f32_16x16x32_bf16 v[26:29], v[162:165], v[202:205], v[26:29]
	v_mfma_f32_16x16x32_bf16 v[18:21], v[154:157], v[210:213], v[18:21]
	v_mfma_f32_16x16x32_bf16 v[10:13], v[162:165], v[210:213], v[10:13]
	v_mfma_f32_16x16x32_bf16 v[62:65], v[158:161], v[190:193], v[62:65]
	v_mfma_f32_16x16x32_bf16 v[58:61], v[166:169], v[190:193], v[58:61]
	v_mfma_f32_16x16x32_bf16 v[50:53], v[158:161], v[198:201], v[50:53]
	v_mfma_f32_16x16x32_bf16 v[42:45], v[166:169], v[198:201], v[42:45]
	v_mfma_f32_16x16x32_bf16 v[34:37], v[158:161], v[206:209], v[34:37]
	v_mfma_f32_16x16x32_bf16 v[26:29], v[166:169], v[206:209], v[26:29]
	v_mfma_f32_16x16x32_bf16 v[18:21], v[158:161], v[214:217], v[18:21]
	v_mfma_f32_16x16x32_bf16 v[10:13], v[166:169], v[214:217], v[10:13]
	s_setprio 0
	s_setprio 1
	v_mfma_f32_16x16x32_bf16 v[54:57], v[170:173], v[186:189], v[54:57]
	v_mfma_f32_16x16x32_bf16 v[46:49], v[178:181], v[186:189], v[46:49]
	v_mfma_f32_16x16x32_bf16 v[38:41], v[170:173], v[194:197], v[38:41]
	v_mfma_f32_16x16x32_bf16 v[30:33], v[178:181], v[194:197], v[30:33]
	v_mfma_f32_16x16x32_bf16 v[22:25], v[170:173], v[202:205], v[22:25]
	v_mfma_f32_16x16x32_bf16 v[14:17], v[178:181], v[202:205], v[14:17]
	v_mfma_f32_16x16x32_bf16 v[6:9], v[170:173], v[210:213], v[6:9]
	v_mfma_f32_16x16x32_bf16 v[2:5], v[178:181], v[210:213], v[2:5]
	v_mfma_f32_16x16x32_bf16 v[54:57], v[174:177], v[190:193], v[54:57]
	v_mfma_f32_16x16x32_bf16 v[46:49], v[182:185], v[190:193], v[46:49]
	v_mfma_f32_16x16x32_bf16 v[38:41], v[174:177], v[198:201], v[38:41]
	v_mfma_f32_16x16x32_bf16 v[30:33], v[182:185], v[198:201], v[30:33]
	v_mfma_f32_16x16x32_bf16 v[22:25], v[174:177], v[206:209], v[22:25]
	v_mfma_f32_16x16x32_bf16 v[14:17], v[182:185], v[206:209], v[14:17]
	v_mfma_f32_16x16x32_bf16 v[6:9], v[174:177], v[214:217], v[6:9]
	v_mfma_f32_16x16x32_bf16 v[2:5], v[182:185], v[214:217], v[2:5]
	s_setprio 0
	s_barrier
; #define PG8_STAGE(bufoff, gbase, voff) do { _Pragma("unroll") for (int _i = 0; _i < 2; ++_i) \
;         __builtin_amdgcn_global_load_lds((const unsigned*)((const char*)(gbase) + (voff)[_i]), (PG8_LAS unsigned*)(lds + (bufoff) + ldsw + _i * 8192), 16, 0, 0); } while (0)
; #define PG8_LDA(dst, b, h) do { _Pragma("unroll") for (int m = 0; m < 4; ++m) _Pragma("unroll") for (int k = 0; k < 2; ++k) dst[m][k] = *(const PG8_LAS bf16x8*)(lds + PG8_SA(b, h) + aoff + m * 2048 + k * 1024); } while (0)
; #define PG8_LDB(dst, b, h) do { _Pragma("unroll") for (int n = 0; n < 2; ++n) _Pragma("unroll") for (int k = 0; k < 2; ++k) dst[n][k] = *(const PG8_LAS bf16x8*)(lds + PG8_SB(b, h) + boff + n * 2048 + k * 1024); } while (0)
; #define PG8_MMA(ai, bj, At, Bt) do { __builtin_amdgcn_s_setprio(1); _Pragma("unroll") for (int m = 0; m < 4; ++m) _Pragma("unroll") for (int n = 0; n < 2; ++n) _Pragma("unroll") for (int k = 0; k < 2; ++k) \
;         acc[ai][bj][m][n] = __builtin_amdgcn_mfma_f32_16x16x32_bf16(Bt[n][k], At[m][k], acc[ai][bj][m][n], 0, 0, 0); __builtin_amdgcn_s_setprio(0); } while (0)
; #define PG8_WAIT_V(n) asm volatile("s_waitcnt vmcnt(" #n ")" ::: "memory")
; #define PG8_WAIT_L(n) asm volatile("s_waitcnt lgkmcnt(" #n ")" ::: "memory")
; #define PG8_BAR __builtin_amdgcn_s_barrier()
; #define PG8_SCHED __builtin_amdgcn_sched_barrier(0)
; template <class Epi, class Sched, bool ALIGN_EPI = false, bool SP2 = false>
; __device__ __forceinline__ void gemm_phase(PG8_LAS unsigned char* lds, const Gemm g, const Sched& S, const Epi& E) {
;     ...
;             PG8_LDB(B0, 1, 0); PG8_LDB(B1, 1, 1); PG8_SCHED; PG8_LDA(At, 1, 0); PG8_STAGE(PG8_SA(0, 1), a2 + hstep, voffA);
;             PG8_WAIT_V(8); PG8_WAIT_L(0); PG8_BAR; PG8_MMA(0, 0, At, B0); PG8_MMA(0, 1, At, B1); PG8_BAR; PG8_SCHED;
;             PG8_LDA(At, 1, 1); PG8_STAGE(PG8_SB(1, 0), b3, voffB); PG8_STAGE(PG8_SB(1, 1), b3 + hstep, voffB); PG8_STAGE(PG8_SA(1, 0), a3, voffA);
;             PG8_WAIT_V(8); PG8_WAIT_L(0); PG8_BAR; PG8_MMA(1, 0, At, B0); PG8_MMA(1, 1, At, B1); PG8_BAR; PG8_SCHED;
	s_add_i32 s30, 0, 0x18000
	v_add_u32_e32 v153, s30, v148
	s_add_i32 s31, 0, 0x1c000
	ds_read_b128 v[154:157], v153
	ds_read_b128 v[158:161], v153 offset:1024
	ds_read_b128 v[162:165], v153 offset:2048
	ds_read_b128 v[166:169], v153 offset:3072
	v_add_u32_e32 v153, s31, v148
	ds_read_b128 v[170:173], v153
	ds_read_b128 v[174:177], v153 offset:1024
	ds_read_b128 v[178:181], v153 offset:2048
	ds_read_b128 v[182:185], v153 offset:3072
	s_add_u32 s4, s38, 0x160000
	s_addc_u32 s5, s39, 0
	s_mov_b32 m0, s51
	ds_read_b128 v[186:189], v152 offset:32768
	ds_read_b128 v[190:193], v152 offset:33792
	ds_read_b128 v[194:197], v152 offset:34816
	ds_read_b128 v[198:201], v152 offset:35840
	ds_read_b128 v[202:205], v152 offset:36864
	ds_read_b128 v[206:209], v152 offset:37888
	ds_read_b128 v[210:213], v152 offset:38912
	ds_read_b128 v[214:217], v152 offset:39936
	global_load_lds_dwordx4 v130, s[4:5]
	s_mov_b32 m0, s52
	s_nop 0
	global_load_lds_dwordx4 v134, s[4:5]
	s_waitcnt vmcnt(8)
	s_waitcnt lgkmcnt(0)
	s_barrier
	s_setprio 1
	s_waitcnt lgkmcnt(0)
	v_mfma_f32_16x16x32_bf16 v[126:129], v[154:157], v[186:189], v[126:129]
	v_mfma_f32_16x16x32_bf16 v[122:125], v[162:165], v[186:189], v[122:125]
	v_mfma_f32_16x16x32_bf16 v[114:117], v[154:157], v[194:197], v[114:117]
	v_mfma_f32_16x16x32_bf16 v[106:109], v[162:165], v[194:197], v[106:109]
	v_mfma_f32_16x16x32_bf16 v[98:101], v[154:157], v[202:205], v[98:101]
	v_mfma_f32_16x16x32_bf16 v[90:93], v[162:165], v[202:205], v[90:93]
	v_mfma_f32_16x16x32_bf16 v[82:85], v[154:157], v[210:213], v[82:85]
	v_mfma_f32_16x16x32_bf16 v[74:77], v[162:165], v[210:213], v[74:77]
	v_mfma_f32_16x16x32_bf16 v[126:129], v[158:161], v[190:193], v[126:129]
	v_mfma_f32_16x16x32_bf16 v[122:125], v[166:169], v[190:193], v[122:125]
	v_mfma_f32_16x16x32_bf16 v[114:117], v[158:161], v[198:201], v[114:117]
	v_mfma_f32_16x16x32_bf16 v[106:109], v[166:169], v[198:201], v[106:109]
	v_mfma_f32_16x16x32_bf16 v[98:101], v[158:161], v[206:209], v[98:101]
	v_mfma_f32_16x16x32_bf16 v[90:93], v[166:169], v[206:209], v[90:93]
	v_mfma_f32_16x16x32_bf16 v[82:85], v[158:161], v[214:217], v[82:85]
	v_mfma_f32_16x16x32_bf16 v[74:77], v[166:169], v[214:217], v[74:77]
	s_setprio 0
	s_setprio 1
	v_mfma_f32_16x16x32_bf16 v[118:121], v[170:173], v[186:189], v[118:121]
	v_mfma_f32_16x16x32_bf16 v[110:113], v[178:181], v[186:189], v[110:113]
	v_mfma_f32_16x16x32_bf16 v[102:105], v[170:173], v[194:197], v[102:105]
	v_mfma_f32_16x16x32_bf16 v[94:97], v[178:181], v[194:197], v[94:97]
	v_mfma_f32_16x16x32_bf16 v[86:89], v[170:173], v[202:205], v[86:89]
	v_mfma_f32_16x16x32_bf16 v[78:81], v[178:181], v[202:205], v[78:81]
	v_mfma_f32_16x16x32_bf16 v[70:73], v[170:173], v[210:213], v[70:73]
	v_mfma_f32_16x16x32_bf16 v[66:69], v[178:181], v[210:213], v[66:69]
	v_mfma_f32_16x16x32_bf16 v[118:121], v[174:177], v[190:193], v[118:121]
	v_mfma_f32_16x16x32_bf16 v[110:113], v[182:185], v[190:193], v[110:113]
	v_mfma_f32_16x16x32_bf16 v[102:105], v[174:177], v[198:201], v[102:105]
	v_mfma_f32_16x16x32_bf16 v[94:97], v[182:185], v[198:201], v[94:97]
	v_mfma_f32_16x16x32_bf16 v[86:89], v[174:177], v[206:209], v[86:89]
	v_mfma_f32_16x16x32_bf16 v[78:81], v[182:185], v[206:209], v[78:81]
	v_mfma_f32_16x16x32_bf16 v[70:73], v[174:177], v[214:217], v[70:73]
	v_mfma_f32_16x16x32_bf16 v[66:69], v[182:185], v[214:217], v[66:69]
	s_setprio 0
	s_barrier
	s_add_i32 s4, s30, s48
	s_add_i32 m0, s4, 0xffffff80
	ds_read_b128 v[186:189], v152 offset:49152
	ds_read_b128 v[190:193], v152 offset:50176
	ds_read_b128 v[194:197], v152 offset:51200
	ds_read_b128 v[198:201], v152 offset:52224
	ds_read_b128 v[202:205], v152 offset:53248
	ds_read_b128 v[206:209], v152 offset:54272
	ds_read_b128 v[210:213], v152 offset:55296
	ds_read_b128 v[214:217], v152 offset:56320
	global_load_lds_dwordx4 v132, s[36:37] offset:128
	s_add_i32 m0, s4, 0x1f80
	s_add_u32 s4, s36, 0x160080
	s_addc_u32 s5, s37, 0
	s_add_i32 s30, s31, s48
	global_load_lds_dwordx4 v136, s[36:37] offset:128
	s_mov_b32 m0, s30
	s_nop 0
	global_load_lds_dwordx4 v132, s[4:5]
	s_add_i32 m0, s30, 0x2000
	s_nop 0
	global_load_lds_dwordx4 v136, s[4:5]
	s_add_i32 m0, s58, 0xffffff80
	s_nop 0
	global_load_lds_dwordx4 v130, s[38:39] offset:128
	s_add_i32 m0, s59, 0xffffff80
	s_nop 0
	global_load_lds_dwordx4 v134, s[38:39] offset:128
	s_waitcnt vmcnt(8)
	s_waitcnt lgkmcnt(0)
	s_barrier
	s_setprio 1
	s_waitcnt lgkmcnt(0)
	v_mfma_f32_16x16x32_bf16 v[62:65], v[154:157], v[186:189], v[62:65]
	v_mfma_f32_16x16x32_bf16 v[58:61], v[162:165], v[186:189], v[58:61]
	v_mfma_f32_16x16x32_bf16 v[50:53], v[154:157], v[194:197], v[50:53]
	v_mfma_f32_16x16x32_bf16 v[42:45], v[162:165], v[194:197], v[42:45]
	v_mfma_f32_16x16x32_bf16 v[34:37], v[154:157], v[202:205], v[34:37]
	v_mfma_f32_16x16x32_bf16 v[26:29], v[162:165], v[202:205], v[26:29]
	v_mfma_f32_16x16x32_bf16 v[18:21], v[154:157], v[210:213], v[18:21]
	v_mfma_f32_16x16x32_bf16 v[10:13], v[162:165], v[210:213], v[10:13]
	v_mfma_f32_16x16x32_bf16 v[62:65], v[158:161], v[190:193], v[62:65]
	v_mfma_f32_16x16x32_bf16 v[58:61], v[166:169], v[190:193], v[58:61]
	v_mfma_f32_16x16x32_bf16 v[50:53], v[158:161], v[198:201], v[50:53]
	v_mfma_f32_16x16x32_bf16 v[42:45], v[166:169], v[198:201], v[42:45]
	v_mfma_f32_16x16x32_bf16 v[34:37], v[158:161], v[206:209], v[34:37]
	v_mfma_f32_16x16x32_bf16 v[26:29], v[166:169], v[206:209], v[26:29]
	v_mfma_f32_16x16x32_bf16 v[18:21], v[158:161], v[214:217], v[18:21]
	v_mfma_f32_16x16x32_bf16 v[10:13], v[166:169], v[214:217], v[10:13]
	s_setprio 0
	s_setprio 1
	v_mfma_f32_16x16x32_bf16 v[54:57], v[170:173], v[186:189], v[54:57]
	v_mfma_f32_16x16x32_bf16 v[46:49], v[178:181], v[186:189], v[46:49]
	v_mfma_f32_16x16x32_bf16 v[38:41], v[170:173], v[194:197], v[38:41]
	v_mfma_f32_16x16x32_bf16 v[30:33], v[178:181], v[194:197], v[30:33]
	v_mfma_f32_16x16x32_bf16 v[22:25], v[170:173], v[202:205], v[22:25]
	v_mfma_f32_16x16x32_bf16 v[14:17], v[178:181], v[202:205], v[14:17]
	v_mfma_f32_16x16x32_bf16 v[6:9], v[170:173], v[210:213], v[6:9]
	v_mfma_f32_16x16x32_bf16 v[2:5], v[178:181], v[210:213], v[2:5]
	v_mfma_f32_16x16x32_bf16 v[54:57], v[174:177], v[190:193], v[54:57]
	v_mfma_f32_16x16x32_bf16 v[46:49], v[182:185], v[190:193], v[46:49]
	v_mfma_f32_16x16x32_bf16 v[38:41], v[174:177], v[198:201], v[38:41]
	v_mfma_f32_16x16x32_bf16 v[30:33], v[182:185], v[198:201], v[30:33]
	v_mfma_f32_16x16x32_bf16 v[22:25], v[174:177], v[206:209], v[22:25]
	v_mfma_f32_16x16x32_bf16 v[14:17], v[182:185], v[206:209], v[14:17]
	v_mfma_f32_16x16x32_bf16 v[6:9], v[174:177], v[214:217], v[6:9]
	v_mfma_f32_16x16x32_bf16 v[2:5], v[182:185], v[214:217], v[2:5]
	s_setprio 0
	s_barrier
	s_add_i32 s74, s74, 2
	s_add_u32 s72, s72, 0x100
	s_addc_u32 s73, s73, 0
	s_cmpk_gt_u32 s74, 0x55
	s_mov_b64 s[30:31], s[34:35]
	s_cbranch_scc0 .LBB0_1017
	s_and_b64 vcc, exec, s[18:19]
	s_cbranch_vccz .LBB0_1020
	s_barrier
